# speedup vs baseline: 1.0181x; 1.0011x over previous
; __device__ __forceinline__ int nblk_opaque() { int t = gridDim.x; asm volatile("" : "+s"(t)); return t; }
; __device__ __forceinline__ int tid_opaque() { int t = threadIdx.x; asm volatile("" : "+v"(t)); return t; }
; template <typename T> __device__ __forceinline__ T* launder(T* p) { asm volatile("" : "+s"(p)); return p; }
; #define STAGE(P, base, kt) do { _Pragma("unroll") for (int _i = 0; _i < 2; ++_i)                                        \
;       __builtin_amdgcn_global_load_lds((const unsigned*)((base) + (size_t)(sOff[_i] + (unsigned)(kt) * (BK * 2))),        \
;                                        (unsigned*)((P) + wid * 1024 + _i * 8192), 16, 0, 0); } while (0)
; #define TILE_BASES(pm_, pn_, a0_, b0_) do {                                                                          \
;     const char* ta_ = (const char*)(A + (size_t)(pm_) * 256 * K); const char* tb_ = (const char*)(Bt + (size_t)(pn_) * 256 * K); \
;     if (EPI == EPI_QKV_A && (pn_) >= 8) { a0_ = tb_; b0_ = ta_; } else { a0_ = ta_; b0_ = tb_; } } while (0)
; template <int EPI, int N, int K>
; __device__ __forceinline__ void phase_gemm(const Params& p, const u16* __restrict__ A, const u16* __restrict__ Bt, int nM, char* shm,
;                            u16* __restrict__ outp, float* __restrict__ rowss) {
;     ...
;   const int tid = tid_opaque(), wid = __builtin_amdgcn_readfirstlane(tid >> 6), lane = tid & 63, wr = wid >> 2, wc = wid & 3, fr = lane & 15, fq = lane >> 4;
;   A = launder(A); Bt = launder(Bt); outp = launder(outp); rowss = launder(rowss);
;   unsigned sOff[2];
; #pragma unroll
;   for (int i = 0; i < 2; ++i) { int R_, C_; stage_rc<2>(wid * 1024 + i * 8192 + lane * 16, R_, C_); sOff[i] = (unsigned)(R_ * K + C_) * 2u; }
;   const int laneoff = (fr * 64 + fq * 16) ^ ((fr >> 3) << 5);
;   const int aoff = wr * 8192 + laneoff;
;   const int boff = wc * 4096 + (fr >> 3) * 2048 + ((512 * ((fr >> 2) & 1) + 64 * (fr & 3) + fq * 16) ^ (((fr >> 2) & 1) << 5));
;   const int nbg = nblk_opaque();
;     ...
;   int v = blockIdx.x;
;   if (v >= nwg) return;
;   int pm, pn;
;   TILE_COORDS(v, pm, pn);
;   const char *A0, *B0p;
;   TILE_BASES(pm, pn, A0, B0p);
;   STAGE(SB(0, 0), B0p, 0); STAGE(SA(0, 0), A0, 0); STAGE(SB(0, 1), B0p + (size_t)128 * K * 2, 0); STAGE(SA(0, 1), A0 + (size_t)128 * K * 2, 0);
;   STAGE(SB(1, 0), B0p, 1); STAGE(SA(1, 0), A0, 1); STAGE(SB(1, 1), B0p + (size_t)128 * K * 2, 1);
.LBB0_124:
	s_lshl_b32 s0, s74, 1
	s_or_b32 s0, s0, 1
	v_readlane_b32 s4, v253, 6
	s_mul_hi_i32 s1, s0, 0xb00000
	s_mul_i32 s0, s0, 0xb00000
	v_readlane_b32 s18, v253, 20
	v_readlane_b32 s52, v253, 22
	v_readlane_b32 s5, v253, 7
	v_readlane_b32 s6, v253, 8
	v_readlane_b32 s7, v253, 9
	v_readlane_b32 s8, v253, 10
	v_readlane_b32 s9, v253, 11
	v_readlane_b32 s19, v253, 21
	s_add_u32 s0, s18, s0
	v_readlane_b32 s62, v253, 32
	v_readlane_b32 s63, v253, 33
	v_readlane_b32 s64, v253, 34
	v_readlane_b32 s65, v253, 35
	s_addc_u32 s1, s19, s1
	v_mov_b32_e32 v0, v184
	s_mov_b64 s[2:3], s[62:63]
	s_mov_b64 s[6:7], s[64:65]
	s_mov_b64 s[4:5], 0
	v_readlane_b32 s8, v253, 61
	v_readlane_b32 s16, v253, 18
	v_readlane_b32 s9, v253, 62
	v_readfirstlane_b32 s16, v0
	v_readlane_b32 s4, v253, 1
	s_andn2_b64 vcc, exec, s[8:9]
	v_readlane_b32 s10, v253, 12
	v_readlane_b32 s11, v253, 13
	v_readlane_b32 s12, v253, 14
	v_readlane_b32 s13, v253, 15
	v_readlane_b32 s14, v253, 16
	v_readlane_b32 s15, v253, 17
	v_readlane_b32 s17, v253, 19
	v_readlane_b32 s53, v253, 23
	v_readlane_b32 s54, v253, 24
	v_readlane_b32 s55, v253, 25
	v_readlane_b32 s56, v253, 26
	v_readlane_b32 s57, v253, 27
	v_readlane_b32 s58, v253, 28
	v_readlane_b32 s59, v253, 29
	v_readlane_b32 s60, v253, 30
	v_readlane_b32 s61, v253, 31
	v_readlane_b32 s66, v253, 36
	v_readlane_b32 s67, v253, 37
	s_cbranch_vccnz .LBB0_136
	s_ashr_i32 s8, s16, 6
	s_waitcnt lgkmcnt(0)
	v_lshlrev_b32_e32 v1, 4, v0
	v_and_b32_e32 v2, 32, v0
	v_lshlrev_b32_e32 v4, 9, v0
	s_lshr_b32 s9, s16, 31
	s_lshl_b32 s5, s8, 10
	v_bitop3_b32 v3, v1, v2, 48 bitop3:0x6c
	v_and_b32_e32 v142, 0x7800, v4
	s_add_i32 s9, s8, s9
	v_or_b32_e32 v3, v3, v142
	s_ashr_i32 s17, s9, 1
	s_and_b32 s9, s9, 0x3fffffe
	s_add_i32 s22, s5, 0x2000
	s_sub_i32 s9, s8, s9
	v_lshl_or_b32 v4, s17, 15, v3
	s_ashr_i32 s18, s22, 10
	v_lshl_add_u32 v96, s9, 6, v4
	s_lshr_b32 s9, s18, 31
	s_add_i32 s9, s18, s9
	s_ashr_i32 s19, s9, 1
	s_and_b32 s9, s9, 0x3fffffe
	s_sub_i32 s9, s18, s9
	v_lshl_or_b32 v3, s19, 15, v3
	s_and_b32 s29, s8, 3
	s_ashr_i32 s30, s16, 8
	v_lshl_add_u32 v130, s9, 6, v3
	s_lshl_b32 s28, s29, 12
	s_lshl_b32 s31, s30, 13
	v_readlane_b32 s8, v254, 3
	v_readlane_b32 s9, v254, 4
	s_add_u32 s8, s0, s8
	s_addc_u32 s9, s1, s9
	s_add_i32 s23, s5, 0x10000
	s_add_i32 s94, s5, 0x12000
	v_readlane_b32 s10, v254, 1
	s_mov_b32 m0, s23
	v_readlane_b32 s11, v254, 2
	s_add_u32 s10, s2, s10
	global_load_lds_dwordx4 v96, s[8:9]
	s_mov_b32 m0, s94
	s_addc_u32 s11, s3, s11
	global_load_lds_dwordx4 v130, s[8:9]
	s_mov_b32 m0, s5
	s_add_u32 s12, s8, 0x40000
	global_load_lds_dwordx4 v96, s[10:11]
	s_mov_b32 m0, s22
	s_addc_u32 s13, s9, 0
	s_add_i32 s95, s5, 0x14000
	s_add_i32 s96, s5, 0x16000
	global_load_lds_dwordx4 v130, s[10:11]
	s_mov_b32 m0, s95
	s_add_u32 s14, s10, 0x40000
	global_load_lds_dwordx4 v96, s[12:13]
	s_mov_b32 m0, s96
	s_addc_u32 s15, s11, 0
	s_add_i32 s97, s5, 0x4000
	global_load_lds_dwordx4 v130, s[12:13]
	s_mov_b32 m0, s97
	s_add_i32 s33, s5, 0x6000
	global_load_lds_dwordx4 v96, s[14:15]
	s_mov_b32 m0, s33
	s_add_i32 s35, s5, 0x18000
	global_load_lds_dwordx4 v130, s[14:15]
	v_add_u32_e32 v132, 0x80, v96
	s_mov_b32 m0, s35
	s_add_i32 s93, s5, 0x1a000
	global_load_lds_dwordx4 v132, s[8:9]
	v_add_u32_e32 v134, 0x80, v130
	s_mov_b32 m0, s93
	s_add_i32 s24, s5, 0x8000
	s_mov_b32 s59, s25
	global_load_lds_dwordx4 v134, s[8:9]
	s_mov_b32 m0, s24
	s_add_i32 s25, s5, 0xa000
	global_load_lds_dwordx4 v132, s[10:11]
	s_mov_b32 m0, s25
	s_add_i32 s26, s5, 0x1c000
	global_load_lds_dwordx4 v134, s[10:11]
	s_mov_b32 m0, s26
	s_add_i32 s27, s5, 0x1e000
	global_load_lds_dwordx4 v132, s[12:13]
	s_mov_b32 m0, s27
	v_lshlrev_b32_e32 v4, 6, v0
	global_load_lds_dwordx4 v134, s[12:13]
	v_bfe_u32 v3, v0, 2, 1
	v_and_b32_e32 v4, 0xc0, v4
	s_cmp_eq_u32 s30, 1
	v_lshl_or_b32 v4, v3, 9, v4
	v_and_b32_e32 v5, 48, v0
	v_lshlrev_b32_e32 v3, 5, v3
	s_cselect_b64 s[12:13], -1, 0
	s_cmpk_lt_u32 s16, 0x100
	v_bitop3_b32 v3, v4, v3, v5 bitop3:0x36
	v_and_b32_e32 v4, 15, v0
	v_bfe_u32 v0, v0, 3, 1
	s_cselect_b64 s[14:15], -1, 0
	s_mulk_i32 s17, 0x7f80
	s_andn2_b32 s16, s16, 63
	v_and_b32_e32 v1, 48, v1
	v_lshlrev_b32_e32 v6, 11, v0
	s_mulk_i32 s19, 0x7f80
	s_lshl_b32 s18, s18, 6
	s_add_i32 s16, s16, s17
	v_or3_b32 v143, s28, v6, v3
	v_lshl_or_b32 v3, v4, 6, v5
	v_lshlrev_b32_e32 v0, 5, v0
	s_add_i32 s18, s18, s19
	v_bitop3_b32 v146, s16, v1, v2 bitop3:0xf6
	v_readlane_b32 s16, v253, 63
	v_bitop3_b32 v144, v3, s31, v0 bitop3:0xde
	v_mov_b32_e32 v131, v97
	v_mov_b32_e32 v133, v97
	v_mov_b32_e32 v135, v97
	s_lshl_b32 s28, s30, 6
	s_lshl_b32 s29, s29, 5
	v_add_u32_e32 v136, 0x780, v96
	v_mov_b32_e32 v137, v97
	v_add_u32_e32 v138, 0x780, v130
	v_mov_b32_e32 v139, v97
	v_bitop3_b32 v145, s18, v1, v2 bitop3:0xf6
	v_readlane_b32 s31, v254, 5
	s_mov_b32 s52, s16
	v_readlane_b32 s30, v253, 0
	s_movk_i32 s58, 0x421
	s_movk_i32 s60, 0xb00
	s_mov_b32 s61, 0x16000
	s_mov_b32 s62, 0x2c000
	s_mov_b32 s63, 0x42000
	s_mov_b32 s64, 0xb0000
	s_mov_b32 s65, 0xc6000
	s_mov_b32 s66, 0xdc000
	v_readlane_b32 s17, v254, 0
	s_waitcnt vmcnt(0)
	s_branch .LBB0_127
; #define SBAR() __builtin_amdgcn_sched_barrier(0)
; template <int EPI, int N, int K>
; __device__ __forceinline__ void phase_gemm(const Params& p, const u16* __restrict__ A, const u16* __restrict__ Bt, int nM, char* shm,
;                            u16* __restrict__ outp, float* __restrict__ rowss) {
;     ...
;     if constexpr (EPI == EPI_SWIGLU) {
;       u16* ob = outp + (size_t)((unsigned)(brow + wr * 64 + fr) * DFF + (unsigned)(pn * 128 + wc * 32 + fq * 8));
; #pragma unroll
;       for (int ai = 0; ai < 2; ++ai)
; #pragma unroll
;         for (int m = 0; m < 4; ++m) {
;           float hv[8];
; #pragma unroll
;           for (int n = 0; n < 2; ++n)
; #pragma unroll
;             for (int j = 0; j < 4; ++j) {
;               float g = acc[ai][0][m][n][j], u = acc[ai][1][m][n][j];
;               hv[n * 4 + j] = g * u * __builtin_amdgcn_rcpf(1.f + __builtin_amdgcn_exp2f(-1.4426950408889634f * g));
;             }
;           u32x4 w = {cvtpk(hv[0], hv[1]), cvtpk(hv[2], hv[3]), cvtpk(hv[4], hv[5]), cvtpk(hv[6], hv[7])};
;           *(u32x4*)(ob + (ai * 128 + m * 16) * DFF) = w;
;           SBAR();
;         }
.LBB0_126:
	v_mul_f32_e32 v118, v114, v118
	v_mul_f32_e32 v114, 0xbfb8aa3b, v114
	v_mul_f32_e32 v126, v122, v126
	v_mul_f32_e32 v122, 0xbfb8aa3b, v122
	v_exp_f32_e32 v114, v114
	v_exp_f32_e32 v122, v122
	s_lshl_b32 s52, s52, 8
	v_mov_b32_e32 v140, v184
	v_add_f32_e32 v114, 1.0, v114
	v_add_f32_e32 v122, 1.0, v122
	v_rcp_f32_e32 v114, v114
	v_rcp_f32_e32 v122, v122
	s_add_i32 s52, s52, s28
	v_mul_f32_e32 v118, v114, v118
	v_mul_f32_e32 v114, v115, v119
	v_mul_f32_e32 v115, 0xbfb8aa3b, v115
	v_mul_f32_e32 v122, v122, v126
	v_mul_f32_e32 v126, v123, v127
	v_mul_f32_e32 v123, 0xbfb8aa3b, v123
	v_exp_f32_e32 v115, v115
	v_exp_f32_e32 v123, v123
	s_lshl_b32 s31, s31, 7
	v_and_or_b32 v141, v140, 15, s52
	v_add_f32_e32 v115, 1.0, v115
	v_add_f32_e32 v123, 1.0, v123
	v_rcp_f32_e32 v115, v115
	v_rcp_f32_e32 v123, v123
	s_or_b32 s31, s31, s29
	v_lshrrev_b32_e32 v140, 1, v140
	v_mul_f32_e32 v119, v115, v114
	v_mul_f32_e32 v115, 0xbfb8aa3b, v116
	v_mul_f32_e32 v123, v123, v126
	v_mul_f32_e32 v126, v124, v128
	v_mul_f32_e32 v124, 0xbfb8aa3b, v124
	v_exp_f32_e32 v115, v115
	v_exp_f32_e32 v124, v124
	v_mul_f32_e32 v114, v116, v120
	v_and_or_b32 v140, v140, 24, s31
	v_add_f32_e32 v115, 1.0, v115
	v_add_f32_e32 v124, 1.0, v124
	v_rcp_f32_e32 v115, v115
	v_rcp_f32_e32 v124, v124
	v_mad_u64_u32 v[140:141], s[52:53], v141, s60, v[140:141]
	v_mul_f32_e32 v120, v115, v114
	v_mul_f32_e32 v115, 0xbfb8aa3b, v117
	v_mul_f32_e32 v124, v124, v126
	v_mul_f32_e32 v126, v125, v129
	v_mul_f32_e32 v125, 0xbfb8aa3b, v125
	v_exp_f32_e32 v115, v115
	v_exp_f32_e32 v125, v125
	v_mov_b32_e32 v141, v97
	v_mul_f32_e32 v114, v117, v121
	v_add_f32_e32 v115, 1.0, v115
	v_add_f32_e32 v125, 1.0, v125
	v_rcp_f32_e32 v115, v115
	v_rcp_f32_e32 v125, v125
	v_lshl_add_u64 v[140:141], v[140:141], 1, s[6:7]
	v_mul_f32_e32 v117, v115, v114
	v_mul_f32_e32 v125, v125, v126
	v_cvt_pk_bf16_f32 v114, v122, v123
	v_cvt_pk_bf16_f32 v115, v124, v125
	v_cvt_pk_bf16_f32 v116, v118, v119
	v_cvt_pk_bf16_f32 v117, v120, v117
	global_store_dwordx4 v[140:141], v[114:117], off
	v_mul_f32_e32 v110, v106, v110
	v_mul_f32_e32 v106, 0xbfb8aa3b, v106
	v_mul_f32_e32 v102, v98, v102
	v_mul_f32_e32 v98, 0xbfb8aa3b, v98
	v_exp_f32_e32 v106, v106
	v_exp_f32_e32 v98, v98
	v_add_f32_e32 v106, 1.0, v106
	v_add_f32_e32 v98, 1.0, v98
	v_rcp_f32_e32 v106, v106
	v_rcp_f32_e32 v98, v98
	v_mul_f32_e32 v106, v106, v110
	v_mul_f32_e32 v110, v107, v111
	v_mul_f32_e32 v107, 0xbfb8aa3b, v107
	v_mul_f32_e32 v102, v98, v102
	v_mul_f32_e32 v98, v99, v103
	v_mul_f32_e32 v99, 0xbfb8aa3b, v99
	v_exp_f32_e32 v107, v107
	v_exp_f32_e32 v99, v99
	v_add_f32_e32 v107, 1.0, v107
	v_add_f32_e32 v99, 1.0, v99
	v_rcp_f32_e32 v107, v107
	v_rcp_f32_e32 v99, v99
	v_mul_f32_e32 v107, v107, v110
	v_mul_f32_e32 v110, v108, v112
	v_mul_f32_e32 v108, 0xbfb8aa3b, v108
	v_mul_f32_e32 v103, v99, v98
	v_mul_f32_e32 v99, 0xbfb8aa3b, v100
	v_exp_f32_e32 v108, v108
	v_exp_f32_e32 v99, v99
	v_mul_f32_e32 v98, v100, v104
	v_add_f32_e32 v108, 1.0, v108
	v_add_f32_e32 v99, 1.0, v99
	v_rcp_f32_e32 v108, v108
	v_rcp_f32_e32 v99, v99
	v_mul_f32_e32 v108, v108, v110
	v_mul_f32_e32 v110, v109, v113
	v_mul_f32_e32 v109, 0xbfb8aa3b, v109
	v_mul_f32_e32 v104, v99, v98
	v_mul_f32_e32 v99, 0xbfb8aa3b, v101
	v_exp_f32_e32 v109, v109
	v_exp_f32_e32 v99, v99
	v_mul_f32_e32 v98, v101, v105
	v_add_f32_e32 v109, 1.0, v109
	v_add_f32_e32 v99, 1.0, v99
	v_rcp_f32_e32 v109, v109
	v_rcp_f32_e32 v99, v99
	v_mul_f32_e32 v109, v109, v110
	v_mul_f32_e32 v101, v99, v98
	v_cvt_pk_bf16_f32 v98, v106, v107
	v_cvt_pk_bf16_f32 v99, v108, v109
	v_cvt_pk_bf16_f32 v100, v102, v103
	v_add_co_u32_e32 v102, vcc, s61, v140
	v_cvt_pk_bf16_f32 v101, v104, v101
	s_nop 1
	v_addc_co_u32_e32 v103, vcc, 0, v141, vcc
	global_store_dwordx4 v[102:103], v[98:101], off
	v_mul_f32_e32 v92, v88, v92
	v_mul_f32_e32 v88, 0xbfb8aa3b, v88
	v_mul_f32_e32 v84, v80, v84
	v_mul_f32_e32 v80, 0xbfb8aa3b, v80
	v_exp_f32_e32 v88, v88
	v_exp_f32_e32 v80, v80
	v_add_f32_e32 v88, 1.0, v88
	v_add_f32_e32 v80, 1.0, v80
	v_rcp_f32_e32 v88, v88
	v_rcp_f32_e32 v80, v80
	v_mul_f32_e32 v88, v88, v92
	v_mul_f32_e32 v92, v89, v93
	v_mul_f32_e32 v89, 0xbfb8aa3b, v89
	v_mul_f32_e32 v84, v80, v84
	v_mul_f32_e32 v80, v81, v85
	v_mul_f32_e32 v81, 0xbfb8aa3b, v81
	v_exp_f32_e32 v89, v89
	v_exp_f32_e32 v81, v81
	v_add_f32_e32 v89, 1.0, v89
	v_add_f32_e32 v81, 1.0, v81
	v_rcp_f32_e32 v89, v89
	v_rcp_f32_e32 v81, v81
	v_mul_f32_e32 v89, v89, v92
	v_mul_f32_e32 v92, v90, v94
	v_mul_f32_e32 v90, 0xbfb8aa3b, v90
	v_mul_f32_e32 v85, v81, v80
	v_mul_f32_e32 v81, 0xbfb8aa3b, v82
	v_exp_f32_e32 v90, v90
	v_exp_f32_e32 v81, v81
	v_mul_f32_e32 v80, v82, v86
	v_add_f32_e32 v90, 1.0, v90
	v_add_f32_e32 v81, 1.0, v81
	v_rcp_f32_e32 v90, v90
	v_rcp_f32_e32 v81, v81
	v_mul_f32_e32 v90, v90, v92
	v_mul_f32_e32 v92, v91, v95
	v_mul_f32_e32 v91, 0xbfb8aa3b, v91
	v_mul_f32_e32 v86, v81, v80
	v_mul_f32_e32 v81, 0xbfb8aa3b, v83
	v_exp_f32_e32 v91, v91
	v_exp_f32_e32 v81, v81
	v_mul_f32_e32 v80, v83, v87
	v_add_f32_e32 v91, 1.0, v91
	v_add_f32_e32 v81, 1.0, v81
	v_rcp_f32_e32 v91, v91
	v_rcp_f32_e32 v81, v81
	v_mul_f32_e32 v91, v91, v92
	v_mul_f32_e32 v83, v81, v80
	v_cvt_pk_bf16_f32 v80, v88, v89
	v_cvt_pk_bf16_f32 v81, v90, v91
	v_cvt_pk_bf16_f32 v82, v84, v85
	v_add_co_u32_e32 v84, vcc, s62, v140
	v_cvt_pk_bf16_f32 v83, v86, v83
	s_nop 1
	v_addc_co_u32_e32 v85, vcc, 0, v141, vcc
	global_store_dwordx4 v[84:85], v[80:83], off
	v_mul_f32_e32 v76, v72, v76
	v_mul_f32_e32 v72, 0xbfb8aa3b, v72
	v_mul_f32_e32 v68, v64, v68
	v_mul_f32_e32 v64, 0xbfb8aa3b, v64
	v_exp_f32_e32 v72, v72
	v_exp_f32_e32 v64, v64
	v_add_f32_e32 v72, 1.0, v72
	v_add_f32_e32 v64, 1.0, v64
; #define SBAR() __builtin_amdgcn_sched_barrier(0)
; template <int EPI, int N, int K>
; __device__ __forceinline__ void phase_gemm(const Params& p, const u16* __restrict__ A, const u16* __restrict__ Bt, int nM, char* shm,
;                            u16* __restrict__ outp, float* __restrict__ rowss) {
;     ...
;     if constexpr (EPI == EPI_SWIGLU) {
;       u16* ob = outp + (size_t)((unsigned)(brow + wr * 64 + fr) * DFF + (unsigned)(pn * 128 + wc * 32 + fq * 8));
; #pragma unroll
;       for (int ai = 0; ai < 2; ++ai)
; #pragma unroll
;         for (int m = 0; m < 4; ++m) {
;           float hv[8];
; #pragma unroll
;           for (int n = 0; n < 2; ++n)
; #pragma unroll
;             for (int j = 0; j < 4; ++j) {
;               float g = acc[ai][0][m][n][j], u = acc[ai][1][m][n][j];
;               hv[n * 4 + j] = g * u * __builtin_amdgcn_rcpf(1.f + __builtin_amdgcn_exp2f(-1.4426950408889634f * g));
;             }
;           u32x4 w = {cvtpk(hv[0], hv[1]), cvtpk(hv[2], hv[3]), cvtpk(hv[4], hv[5]), cvtpk(hv[6], hv[7])};
;           *(u32x4*)(ob + (ai * 128 + m * 16) * DFF) = w;
;           SBAR();
;         }
	v_rcp_f32_e32 v72, v72
	v_rcp_f32_e32 v64, v64
	v_mul_f32_e32 v72, v72, v76
	v_mul_f32_e32 v76, v73, v77
	v_mul_f32_e32 v73, 0xbfb8aa3b, v73
	v_mul_f32_e32 v68, v64, v68
	v_mul_f32_e32 v64, v65, v69
	v_mul_f32_e32 v65, 0xbfb8aa3b, v65
	v_exp_f32_e32 v73, v73
	v_exp_f32_e32 v65, v65
	v_add_f32_e32 v73, 1.0, v73
	v_add_f32_e32 v65, 1.0, v65
	v_rcp_f32_e32 v73, v73
	v_rcp_f32_e32 v65, v65
	v_mul_f32_e32 v73, v73, v76
	v_mul_f32_e32 v76, v74, v78
	v_mul_f32_e32 v74, 0xbfb8aa3b, v74
	v_mul_f32_e32 v69, v65, v64
	v_mul_f32_e32 v65, 0xbfb8aa3b, v66
	v_exp_f32_e32 v74, v74
	v_exp_f32_e32 v65, v65
	v_mul_f32_e32 v64, v66, v70
	v_add_f32_e32 v74, 1.0, v74
	v_add_f32_e32 v65, 1.0, v65
	v_rcp_f32_e32 v74, v74
	v_rcp_f32_e32 v65, v65
	v_mul_f32_e32 v74, v74, v76
	v_mul_f32_e32 v76, v75, v79
	v_mul_f32_e32 v75, 0xbfb8aa3b, v75
	v_mul_f32_e32 v70, v65, v64
	v_mul_f32_e32 v65, 0xbfb8aa3b, v67
	v_exp_f32_e32 v75, v75
	v_exp_f32_e32 v65, v65
	v_mul_f32_e32 v64, v67, v71
	v_add_f32_e32 v75, 1.0, v75
	v_add_f32_e32 v65, 1.0, v65
	v_rcp_f32_e32 v75, v75
	v_rcp_f32_e32 v65, v65
	v_mul_f32_e32 v75, v75, v76
	v_mul_f32_e32 v67, v65, v64
	v_cvt_pk_bf16_f32 v64, v72, v73
	v_cvt_pk_bf16_f32 v65, v74, v75
	v_cvt_pk_bf16_f32 v66, v68, v69
	v_add_co_u32_e32 v68, vcc, s63, v140
	v_cvt_pk_bf16_f32 v67, v70, v67
	s_nop 1
	v_addc_co_u32_e32 v69, vcc, 0, v141, vcc
	global_store_dwordx4 v[68:69], v[64:67], off
	v_mul_f32_e32 v60, v56, v60
	v_mul_f32_e32 v56, 0xbfb8aa3b, v56
	v_mul_f32_e32 v52, v48, v52
	v_mul_f32_e32 v48, 0xbfb8aa3b, v48
	v_exp_f32_e32 v56, v56
	v_exp_f32_e32 v48, v48
	v_add_f32_e32 v56, 1.0, v56
	v_add_f32_e32 v48, 1.0, v48
	v_rcp_f32_e32 v56, v56
	v_rcp_f32_e32 v48, v48
	v_mul_f32_e32 v56, v56, v60
	v_mul_f32_e32 v60, v57, v61
	v_mul_f32_e32 v57, 0xbfb8aa3b, v57
	v_mul_f32_e32 v52, v48, v52
	v_mul_f32_e32 v48, v49, v53
	v_mul_f32_e32 v49, 0xbfb8aa3b, v49
	v_exp_f32_e32 v57, v57
	v_exp_f32_e32 v49, v49
	v_add_f32_e32 v57, 1.0, v57
	v_add_f32_e32 v49, 1.0, v49
	v_rcp_f32_e32 v57, v57
	v_rcp_f32_e32 v49, v49
	v_mul_f32_e32 v57, v57, v60
	v_mul_f32_e32 v60, v58, v62
	v_mul_f32_e32 v58, 0xbfb8aa3b, v58
	v_mul_f32_e32 v53, v49, v48
	v_mul_f32_e32 v49, 0xbfb8aa3b, v50
	v_exp_f32_e32 v58, v58
	v_exp_f32_e32 v49, v49
	v_mul_f32_e32 v48, v50, v54
	v_add_f32_e32 v58, 1.0, v58
	v_add_f32_e32 v49, 1.0, v49
	v_rcp_f32_e32 v58, v58
	v_rcp_f32_e32 v49, v49
	v_mul_f32_e32 v58, v58, v60
	v_mul_f32_e32 v60, v59, v63
	v_mul_f32_e32 v59, 0xbfb8aa3b, v59
	v_mul_f32_e32 v54, v49, v48
	v_mul_f32_e32 v49, 0xbfb8aa3b, v51
	v_exp_f32_e32 v59, v59
	v_exp_f32_e32 v49, v49
	v_mul_f32_e32 v48, v51, v55
	v_add_f32_e32 v59, 1.0, v59
	v_add_f32_e32 v49, 1.0, v49
	v_rcp_f32_e32 v59, v59
	v_rcp_f32_e32 v49, v49
	v_mul_f32_e32 v59, v59, v60
	v_mul_f32_e32 v51, v49, v48
	v_cvt_pk_bf16_f32 v48, v56, v57
	v_cvt_pk_bf16_f32 v49, v58, v59
	v_cvt_pk_bf16_f32 v50, v52, v53
	v_add_co_u32_e32 v52, vcc, s64, v140
	v_cvt_pk_bf16_f32 v51, v54, v51
	s_nop 1
	v_addc_co_u32_e32 v53, vcc, 0, v141, vcc
	global_store_dwordx4 v[52:53], v[48:51], off
	v_mul_f32_e32 v44, v40, v44
	v_mul_f32_e32 v40, 0xbfb8aa3b, v40
	v_mul_f32_e32 v36, v32, v36
	v_mul_f32_e32 v32, 0xbfb8aa3b, v32
	v_exp_f32_e32 v40, v40
	v_exp_f32_e32 v32, v32
	v_add_f32_e32 v40, 1.0, v40
	v_add_f32_e32 v32, 1.0, v32
	v_rcp_f32_e32 v40, v40
	v_rcp_f32_e32 v32, v32
	v_mul_f32_e32 v40, v40, v44
	v_mul_f32_e32 v44, v41, v45
	v_mul_f32_e32 v41, 0xbfb8aa3b, v41
	v_mul_f32_e32 v36, v32, v36
	v_mul_f32_e32 v32, v33, v37
	v_mul_f32_e32 v33, 0xbfb8aa3b, v33
	v_exp_f32_e32 v41, v41
	v_exp_f32_e32 v33, v33
	v_add_f32_e32 v41, 1.0, v41
	v_add_f32_e32 v33, 1.0, v33
	v_rcp_f32_e32 v41, v41
	v_rcp_f32_e32 v33, v33
	v_mul_f32_e32 v41, v41, v44
	v_mul_f32_e32 v44, v42, v46
	v_mul_f32_e32 v42, 0xbfb8aa3b, v42
	v_mul_f32_e32 v37, v33, v32
	v_mul_f32_e32 v33, 0xbfb8aa3b, v34
	v_exp_f32_e32 v42, v42
	v_exp_f32_e32 v33, v33
	v_mul_f32_e32 v32, v34, v38
	v_add_f32_e32 v42, 1.0, v42
	v_add_f32_e32 v33, 1.0, v33
	v_rcp_f32_e32 v42, v42
; #define SBAR() __builtin_amdgcn_sched_barrier(0)
; template <int EPI, int N, int K>
; __device__ __forceinline__ void phase_gemm(const Params& p, const u16* __restrict__ A, const u16* __restrict__ Bt, int nM, char* shm,
;                            u16* __restrict__ outp, float* __restrict__ rowss) {
;     ...
;     if constexpr (EPI == EPI_SWIGLU) {
;       u16* ob = outp + (size_t)((unsigned)(brow + wr * 64 + fr) * DFF + (unsigned)(pn * 128 + wc * 32 + fq * 8));
; #pragma unroll
;       for (int ai = 0; ai < 2; ++ai)
; #pragma unroll
;         for (int m = 0; m < 4; ++m) {
;           float hv[8];
; #pragma unroll
;           for (int n = 0; n < 2; ++n)
; #pragma unroll
;             for (int j = 0; j < 4; ++j) {
;               float g = acc[ai][0][m][n][j], u = acc[ai][1][m][n][j];
;               hv[n * 4 + j] = g * u * __builtin_amdgcn_rcpf(1.f + __builtin_amdgcn_exp2f(-1.4426950408889634f * g));
;             }
;           u32x4 w = {cvtpk(hv[0], hv[1]), cvtpk(hv[2], hv[3]), cvtpk(hv[4], hv[5]), cvtpk(hv[6], hv[7])};
;           *(u32x4*)(ob + (ai * 128 + m * 16) * DFF) = w;
;           SBAR();
;         }
;     ...
;     if (!more) break;
;     v = vn; pm = pmn; pn = pnn; A0 = A0n; B0p = B0n;
	v_rcp_f32_e32 v33, v33
	v_mul_f32_e32 v42, v42, v44
	v_mul_f32_e32 v44, v43, v47
	v_mul_f32_e32 v43, 0xbfb8aa3b, v43
	v_mul_f32_e32 v38, v33, v32
	v_mul_f32_e32 v33, 0xbfb8aa3b, v35
	v_exp_f32_e32 v43, v43
	v_exp_f32_e32 v33, v33
	v_mul_f32_e32 v32, v35, v39
	v_add_f32_e32 v43, 1.0, v43
	v_add_f32_e32 v33, 1.0, v33
	v_rcp_f32_e32 v43, v43
	v_rcp_f32_e32 v33, v33
	v_mul_f32_e32 v43, v43, v44
	v_mul_f32_e32 v35, v33, v32
	v_cvt_pk_bf16_f32 v32, v40, v41
	v_cvt_pk_bf16_f32 v33, v42, v43
	v_cvt_pk_bf16_f32 v34, v36, v37
	v_add_co_u32_e32 v36, vcc, s65, v140
	v_cvt_pk_bf16_f32 v35, v38, v35
	s_nop 1
	v_addc_co_u32_e32 v37, vcc, 0, v141, vcc
	global_store_dwordx4 v[36:37], v[32:35], off
	v_mul_f32_e32 v28, v24, v28
	v_mul_f32_e32 v24, 0xbfb8aa3b, v24
	v_mul_f32_e32 v20, v16, v20
	v_mul_f32_e32 v16, 0xbfb8aa3b, v16
	v_exp_f32_e32 v24, v24
	v_exp_f32_e32 v16, v16
	v_add_f32_e32 v24, 1.0, v24
	v_add_f32_e32 v16, 1.0, v16
	v_rcp_f32_e32 v24, v24
	v_rcp_f32_e32 v16, v16
	v_mul_f32_e32 v24, v24, v28
	v_mul_f32_e32 v28, v25, v29
	v_mul_f32_e32 v25, 0xbfb8aa3b, v25
	v_mul_f32_e32 v20, v16, v20
	v_mul_f32_e32 v16, v17, v21
	v_mul_f32_e32 v17, 0xbfb8aa3b, v17
	v_exp_f32_e32 v25, v25
	v_exp_f32_e32 v17, v17
	v_add_f32_e32 v25, 1.0, v25
	v_add_f32_e32 v17, 1.0, v17
	v_rcp_f32_e32 v25, v25
	v_rcp_f32_e32 v17, v17
	v_mul_f32_e32 v25, v25, v28
	v_mul_f32_e32 v28, v26, v30
	v_mul_f32_e32 v26, 0xbfb8aa3b, v26
	v_mul_f32_e32 v21, v17, v16
	v_mul_f32_e32 v17, 0xbfb8aa3b, v18
	v_exp_f32_e32 v26, v26
	v_exp_f32_e32 v17, v17
	v_mul_f32_e32 v16, v18, v22
	v_add_f32_e32 v26, 1.0, v26
	v_add_f32_e32 v17, 1.0, v17
	v_rcp_f32_e32 v26, v26
	v_rcp_f32_e32 v17, v17
	v_mul_f32_e32 v26, v26, v28
	v_mul_f32_e32 v28, v27, v31
	v_mul_f32_e32 v27, 0xbfb8aa3b, v27
	v_mul_f32_e32 v22, v17, v16
	v_mul_f32_e32 v17, 0xbfb8aa3b, v19
	v_exp_f32_e32 v27, v27
	v_exp_f32_e32 v17, v17
	v_mul_f32_e32 v16, v19, v23
	v_add_f32_e32 v27, 1.0, v27
	v_add_f32_e32 v17, 1.0, v17
	v_rcp_f32_e32 v27, v27
	v_rcp_f32_e32 v17, v17
	v_mul_f32_e32 v27, v27, v28
	v_mul_f32_e32 v19, v17, v16
	v_cvt_pk_bf16_f32 v16, v24, v25
	v_cvt_pk_bf16_f32 v17, v26, v27
	v_cvt_pk_bf16_f32 v18, v20, v21
	v_add_co_u32_e32 v20, vcc, s66, v140
	v_cvt_pk_bf16_f32 v19, v22, v19
	s_nop 1
	v_addc_co_u32_e32 v21, vcc, 0, v141, vcc
	global_store_dwordx4 v[20:21], v[16:19], off
	v_mul_f32_e32 v12, v8, v12
	v_mul_f32_e32 v8, 0xbfb8aa3b, v8
	v_mul_f32_e32 v4, v0, v4
	v_mul_f32_e32 v0, 0xbfb8aa3b, v0
	v_exp_f32_e32 v8, v8
	v_exp_f32_e32 v0, v0
	v_add_f32_e32 v8, 1.0, v8
	v_add_f32_e32 v0, 1.0, v0
	v_rcp_f32_e32 v8, v8
	v_rcp_f32_e32 v0, v0
	v_mul_f32_e32 v8, v8, v12
	v_mul_f32_e32 v12, v9, v13
	v_mul_f32_e32 v9, 0xbfb8aa3b, v9
	v_mul_f32_e32 v4, v0, v4
	v_mul_f32_e32 v0, v1, v5
	v_mul_f32_e32 v1, 0xbfb8aa3b, v1
	v_exp_f32_e32 v9, v9
	v_exp_f32_e32 v1, v1
	v_add_f32_e32 v9, 1.0, v9
	v_add_f32_e32 v1, 1.0, v1
	v_rcp_f32_e32 v9, v9
	v_rcp_f32_e32 v1, v1
	v_mul_f32_e32 v9, v9, v12
	v_mul_f32_e32 v12, v10, v14
	v_mul_f32_e32 v10, 0xbfb8aa3b, v10
	v_mul_f32_e32 v5, v1, v0
	v_mul_f32_e32 v1, 0xbfb8aa3b, v2
	v_exp_f32_e32 v10, v10
	v_exp_f32_e32 v1, v1
	v_mul_f32_e32 v0, v2, v6
	v_add_f32_e32 v10, 1.0, v10
	v_add_f32_e32 v1, 1.0, v1
	v_rcp_f32_e32 v10, v10
	v_rcp_f32_e32 v1, v1
	v_mul_f32_e32 v10, v10, v12
	v_mul_f32_e32 v12, v11, v15
	v_mul_f32_e32 v11, 0xbfb8aa3b, v11
	v_mul_f32_e32 v6, v1, v0
	v_mul_f32_e32 v1, 0xbfb8aa3b, v3
	v_exp_f32_e32 v11, v11
	v_exp_f32_e32 v1, v1
	v_mul_f32_e32 v0, v3, v7
	v_add_f32_e32 v11, 1.0, v11
	v_add_f32_e32 v1, 1.0, v1
	v_rcp_f32_e32 v11, v11
	v_rcp_f32_e32 v1, v1
	v_mul_f32_e32 v11, v11, v12
	v_mul_f32_e32 v3, v1, v0
	v_cvt_pk_bf16_f32 v0, v8, v9
	v_cvt_pk_bf16_f32 v1, v10, v11
	v_cvt_pk_bf16_f32 v2, v4, v5
	v_add_co_u32_e32 v4, vcc, 0xf2000, v140
	v_cvt_pk_bf16_f32 v3, v6, v3
	s_nop 1
	v_addc_co_u32_e32 v5, vcc, 0, v141, vcc
	global_store_dwordx4 v[4:5], v[0:3], off
	s_andn2_b64 vcc, exec, s[16:17]
	s_mov_b32 s31, s19
	s_mov_b32 s52, s18
	s_cbranch_vccz .LBB0_135
	s_waitcnt vmcnt(8)

; #define WAIT_V(n) asm volatile("s_waitcnt vmcnt(%0)" ::"n"(n) : "memory")
; #define WAIT_L(n) asm volatile("s_waitcnt lgkmcnt(%0)" ::"n"(n) : "memory")
; #define SBAR() __builtin_amdgcn_sched_barrier(0)
; #define STAGE(P, base, kt) do { _Pragma("unroll") for (int _i = 0; _i < 2; ++_i)                                        \
;       __builtin_amdgcn_global_load_lds((const unsigned*)((base) + (size_t)(sOff[_i] + (unsigned)(kt) * (BK * 2))),        \
;                                        (unsigned*)((P) + wid * 1024 + _i * 8192), 16, 0, 0); } while (0)
; #define LDA(dst, b, h) _Pragma("unroll") for (int m = 0; m < 4; ++m) _Pragma("unroll") for (int k = 0; k < 2; ++k) \
;       dst[m][k] = *(const bf16x8*)(SA(b, h) + aoff + (m * 2048 + k * 1024))
; #define LDB(dst, b, h) _Pragma("unroll") for (int n = 0; n < 2; ++n) _Pragma("unroll") for (int k = 0; k < 2; ++k) \
;       dst[n][k] = *(const bf16x8*)(SB(b, h) + boff + (n * 256 + k * 1024))
; #define BAR __builtin_amdgcn_s_barrier()
; template <int EPI, int N, int K>
; __device__ __forceinline__ void phase_gemm(const Params& p, const u16* __restrict__ A, const u16* __restrict__ Bt, int nM, char* shm,
;                            u16* __restrict__ outp, float* __restrict__ rowss) {
;     ...
;   for (;;) {
;     const char* A1 = A0 + (size_t)128 * K * 2;
;     const char* B1p = B0p + (size_t)128 * K * 2;
;     f32x4 acc[2][2][4][2] = {};
;     bf16x8 At[4][2], B0[2][2], B1[2][2];
;     if (wr == 1) BAR;
;     WAIT_V(0); BAR;
;     BAR;
;     for (int t = 0; t < nt - 2; t += 2) {
;       LDB(B0, 0, 0); SBAR(); LDA(At, 0, 0); STAGE(SA(1, 1), A1, t + 1);
;       WAIT_L(8); BAR; WAIT_L(0); MMA(0, 0, At, B0); BAR; SBAR();
;       LDB(B1, 0, 1); STAGE(SB(0, 0), B0p, t + 2);
;       BAR; WAIT_L(0); MMA(0, 1, At, B1); BAR;
;       LDA(At, 0, 1); STAGE(SA(0, 0), A0, t + 2);
;       BAR; WAIT_L(0); MMA(1, 0, At, B0); BAR; SBAR();
;       STAGE(SB(0, 1), B1p, t + 2);
;       WAIT_V(6); BAR; MMA(1, 1, At, B1); BAR;
.LBB0_129:
	s_add_u32 s16, s10, 0x40000
	s_addc_u32 s17, s11, 0
	s_add_u32 s18, s8, 0x40000
	s_addc_u32 s19, s9, 0
	s_mov_b32 s53, -2
	v_mov_b32_e32 v140, v146
	v_mov_b32_e32 v141, v145
	s_barrier
	s_barrier
	v_or_b32_e32 v147, 0x10000, v143
	v_add_u32_e32 v149, 0x10100, v143
	v_add_u32_e32 v148, 0x10400, v143
	ds_read_b128 v[156:159], v147
	ds_read_b128 v[160:163], v148
	v_add_u32_e32 v150, 0x10500, v143
	ds_read_b128 v[164:167], v149
	ds_read_b128 v[168:171], v150
	v_add_u32_e32 v240, v142, v140
	s_add_i32 s55, s5, 0xc000
	v_add_u32_e32 v151, 0x80, v240
	s_mov_b32 m0, s55
	v_add_u32_e32 v241, v142, v141
	s_add_i32 s54, s5, 0xe000
	ds_read_b128 v[172:175], v144
	ds_read_b128 v[176:179], v144 offset:1024
	ds_read_b128 v[180:183], v144 offset:2048
	ds_read_b128 v[196:199], v144 offset:3072
	ds_read_b128 v[200:203], v144 offset:4096
	ds_read_b128 v[204:207], v144 offset:5120
	ds_read_b128 v[208:211], v144 offset:6144
	ds_read_b128 v[212:215], v144 offset:7168
	global_load_lds_dwordx4 v151, s[16:17]
	v_add_u32_e32 v151, 0x80, v241
	s_mov_b32 m0, s54
	s_nop 0
	global_load_lds_dwordx4 v151, s[16:17]
	s_waitcnt lgkmcnt(8)
	s_barrier
	s_waitcnt lgkmcnt(0)
	s_waitcnt lgkmcnt(0)
	v_mfma_f32_16x16x32_bf16 v[126:129], v[156:159], v[172:175], 0
	v_mfma_f32_16x16x32_bf16 v[122:125], v[164:167], v[172:175], 0
	v_mfma_f32_16x16x32_bf16 v[118:121], v[156:159], v[180:183], 0
	v_mfma_f32_16x16x32_bf16 v[114:117], v[164:167], v[180:183], 0
	v_mfma_f32_16x16x32_bf16 v[110:113], v[156:159], v[200:203], 0
	v_mfma_f32_16x16x32_bf16 v[106:109], v[164:167], v[200:203], 0
	v_mfma_f32_16x16x32_bf16 v[102:105], v[156:159], v[208:211], 0
	v_mfma_f32_16x16x32_bf16 v[98:101], v[164:167], v[208:211], 0
	v_mfma_f32_16x16x32_bf16 v[126:129], v[160:163], v[176:179], v[126:129]
	v_mfma_f32_16x16x32_bf16 v[122:125], v[168:171], v[176:179], v[122:125]
	v_mfma_f32_16x16x32_bf16 v[118:121], v[160:163], v[196:199], v[118:121]
	v_mfma_f32_16x16x32_bf16 v[114:117], v[168:171], v[196:199], v[114:117]
	v_mfma_f32_16x16x32_bf16 v[110:113], v[160:163], v[204:207], v[110:113]
	v_mfma_f32_16x16x32_bf16 v[106:109], v[168:171], v[204:207], v[106:109]
	v_mfma_f32_16x16x32_bf16 v[102:105], v[160:163], v[212:215], v[102:105]
	v_mfma_f32_16x16x32_bf16 v[98:101], v[168:171], v[212:215], v[98:101]
	s_barrier
	s_mov_b32 m0, s23
	v_or_b32_e32 v151, 0x14000, v143
	v_add_u32_e32 v153, 0x14100, v143
	v_add_u32_e32 v232, 0x100, v240
	v_add_u32_e32 v152, 0x14400, v143
	ds_read_b128 v[216:219], v151
	ds_read_b128 v[220:223], v152
	v_add_u32_e32 v154, 0x14500, v143
	ds_read_b128 v[224:227], v153
	ds_read_b128 v[228:231], v154
	global_load_lds_dwordx4 v232, s[8:9]
	v_add_u32_e32 v233, 0x100, v241
	s_mov_b32 m0, s94
	s_nop 0
	global_load_lds_dwordx4 v233, s[8:9]
	s_barrier
	s_waitcnt lgkmcnt(0)
	s_waitcnt lgkmcnt(0)
	v_mfma_f32_16x16x32_bf16 v[92:95], v[216:219], v[172:175], 0
	v_mfma_f32_16x16x32_bf16 v[88:91], v[224:227], v[172:175], 0
	v_mfma_f32_16x16x32_bf16 v[84:87], v[216:219], v[180:183], 0
	v_mfma_f32_16x16x32_bf16 v[80:83], v[224:227], v[180:183], 0
	v_mfma_f32_16x16x32_bf16 v[76:79], v[216:219], v[200:203], 0
	v_mfma_f32_16x16x32_bf16 v[72:75], v[224:227], v[200:203], 0
	v_mfma_f32_16x16x32_bf16 v[68:71], v[216:219], v[208:211], 0
	v_mfma_f32_16x16x32_bf16 v[64:67], v[224:227], v[208:211], 0
	v_mfma_f32_16x16x32_bf16 v[92:95], v[220:223], v[176:179], v[92:95]
	v_mfma_f32_16x16x32_bf16 v[88:91], v[228:231], v[176:179], v[88:91]
	v_mfma_f32_16x16x32_bf16 v[84:87], v[220:223], v[196:199], v[84:87]
	v_mfma_f32_16x16x32_bf16 v[80:83], v[228:231], v[196:199], v[80:83]
	v_mfma_f32_16x16x32_bf16 v[76:79], v[220:223], v[204:207], v[76:79]
	v_mfma_f32_16x16x32_bf16 v[72:75], v[228:231], v[204:207], v[72:75]
	v_mfma_f32_16x16x32_bf16 v[68:71], v[220:223], v[212:215], v[68:71]
	v_mfma_f32_16x16x32_bf16 v[64:67], v[228:231], v[212:215], v[64:67]
	s_mov_b32 m0, s5
	s_barrier
	ds_read_b128 v[172:175], v144 offset:16384
	ds_read_b128 v[176:179], v144 offset:17408
	ds_read_b128 v[180:183], v144 offset:18432
	ds_read_b128 v[196:199], v144 offset:19456
	ds_read_b128 v[200:203], v144 offset:20480
	ds_read_b128 v[204:207], v144 offset:21504
	ds_read_b128 v[208:211], v144 offset:22528
	ds_read_b128 v[212:215], v144 offset:23552
	global_load_lds_dwordx4 v232, s[10:11]
	s_mov_b32 m0, s22
	s_nop 0
	global_load_lds_dwordx4 v233, s[10:11]
	s_barrier
	s_waitcnt lgkmcnt(0)
	s_waitcnt lgkmcnt(0)
	v_mfma_f32_16x16x32_bf16 v[60:63], v[156:159], v[172:175], 0
	v_mfma_f32_16x16x32_bf16 v[56:59], v[164:167], v[172:175], 0
	v_mfma_f32_16x16x32_bf16 v[52:55], v[156:159], v[180:183], 0
	v_mfma_f32_16x16x32_bf16 v[48:51], v[164:167], v[180:183], 0
	v_mfma_f32_16x16x32_bf16 v[44:47], v[156:159], v[200:203], 0
	v_mfma_f32_16x16x32_bf16 v[40:43], v[164:167], v[200:203], 0
	v_mfma_f32_16x16x32_bf16 v[36:39], v[156:159], v[208:211], 0
	v_mfma_f32_16x16x32_bf16 v[32:35], v[164:167], v[208:211], 0
	v_mfma_f32_16x16x32_bf16 v[60:63], v[160:163], v[176:179], v[60:63]
	v_mfma_f32_16x16x32_bf16 v[56:59], v[168:171], v[176:179], v[56:59]
	v_mfma_f32_16x16x32_bf16 v[52:55], v[160:163], v[196:199], v[52:55]
	v_mfma_f32_16x16x32_bf16 v[48:51], v[168:171], v[196:199], v[48:51]
	v_mfma_f32_16x16x32_bf16 v[44:47], v[160:163], v[204:207], v[44:47]
	v_mfma_f32_16x16x32_bf16 v[40:43], v[168:171], v[204:207], v[40:43]
	v_mfma_f32_16x16x32_bf16 v[36:39], v[160:163], v[212:215], v[36:39]
	v_mfma_f32_16x16x32_bf16 v[32:35], v[168:171], v[212:215], v[32:35]
	s_barrier
	s_mov_b32 m0, s95
	s_nop 0
	global_load_lds_dwordx4 v232, s[18:19]
	s_mov_b32 m0, s96
	s_nop 0
	global_load_lds_dwordx4 v233, s[18:19]
	s_waitcnt vmcnt(6)
	s_barrier
; #define WAIT_V(n) asm volatile("s_waitcnt vmcnt(%0)" ::"n"(n) : "memory")
; #define WAIT_L(n) asm volatile("s_waitcnt lgkmcnt(%0)" ::"n"(n) : "memory")
; #define SBAR() __builtin_amdgcn_sched_barrier(0)
; #define STAGE(P, base, kt) do { _Pragma("unroll") for (int _i = 0; _i < 2; ++_i)                                        \
;       __builtin_amdgcn_global_load_lds((const unsigned*)((base) + (size_t)(sOff[_i] + (unsigned)(kt) * (BK * 2))),        \
;                                        (unsigned*)((P) + wid * 1024 + _i * 8192), 16, 0, 0); } while (0)
; #define LDA(dst, b, h) _Pragma("unroll") for (int m = 0; m < 4; ++m) _Pragma("unroll") for (int k = 0; k < 2; ++k) \
;       dst[m][k] = *(const bf16x8*)(SA(b, h) + aoff + (m * 2048 + k * 1024))
; #define LDB(dst, b, h) _Pragma("unroll") for (int n = 0; n < 2; ++n) _Pragma("unroll") for (int k = 0; k < 2; ++k) \
;       dst[n][k] = *(const bf16x8*)(SB(b, h) + boff + (n * 256 + k * 1024))
; #define BAR __builtin_amdgcn_s_barrier()
; template <int EPI, int N, int K>
; __device__ __forceinline__ void phase_gemm(const Params& p, const u16* __restrict__ A, const u16* __restrict__ Bt, int nM, char* shm,
;                            u16* __restrict__ outp, float* __restrict__ rowss) {
;     ...
;       WAIT_V(6); BAR; MMA(1, 1, At, B1); BAR;
;       LDB(B0, 1, 0); SBAR(); LDA(At, 1, 0); STAGE(SA(0, 1), A1, t + 2);
;       WAIT_L(8); BAR; WAIT_L(0); MMA(0, 0, At, B0); BAR; SBAR();
;       LDB(B1, 1, 1); STAGE(SB(1, 0), B0p, t + 3);
;       BAR; WAIT_L(0); MMA(0, 1, At, B1); BAR;
;       LDA(At, 1, 1); STAGE(SA(1, 0), A0, t + 3);
;       BAR; WAIT_L(0); MMA(1, 0, At, B0); BAR; SBAR();
	v_mfma_f32_16x16x32_bf16 v[28:31], v[216:219], v[172:175], 0
	v_mfma_f32_16x16x32_bf16 v[24:27], v[224:227], v[172:175], 0
	v_mfma_f32_16x16x32_bf16 v[20:23], v[216:219], v[180:183], 0
	v_mfma_f32_16x16x32_bf16 v[16:19], v[224:227], v[180:183], 0
	v_mfma_f32_16x16x32_bf16 v[12:15], v[216:219], v[200:203], 0
	v_mfma_f32_16x16x32_bf16 v[8:11], v[224:227], v[200:203], 0
	v_mfma_f32_16x16x32_bf16 v[4:7], v[216:219], v[208:211], 0
	v_mfma_f32_16x16x32_bf16 v[0:3], v[224:227], v[208:211], 0
	v_mfma_f32_16x16x32_bf16 v[28:31], v[220:223], v[176:179], v[28:31]
	v_mfma_f32_16x16x32_bf16 v[24:27], v[228:231], v[176:179], v[24:27]
	v_mfma_f32_16x16x32_bf16 v[20:23], v[220:223], v[196:199], v[20:23]
	v_mfma_f32_16x16x32_bf16 v[16:19], v[228:231], v[196:199], v[16:19]
	v_mfma_f32_16x16x32_bf16 v[12:15], v[220:223], v[204:207], v[12:15]
	v_mfma_f32_16x16x32_bf16 v[8:11], v[228:231], v[204:207], v[8:11]
	v_mfma_f32_16x16x32_bf16 v[4:7], v[220:223], v[212:215], v[4:7]
	v_mfma_f32_16x16x32_bf16 v[0:3], v[228:231], v[212:215], v[0:3]
	v_or_b32_e32 v155, 0x18000, v143
	v_add_u32_e32 v157, 0x18100, v143
	s_barrier
	v_add_u32_e32 v156, 0x18400, v143
	ds_read_b128 v[164:167], v155
	ds_read_b128 v[168:171], v156
	v_add_u32_e32 v158, 0x18500, v143
	ds_read_b128 v[172:175], v157
	ds_read_b128 v[176:179], v158
	s_mov_b32 m0, s97
	ds_read_b128 v[180:183], v144 offset:32768
	ds_read_b128 v[196:199], v144 offset:33792
	ds_read_b128 v[200:203], v144 offset:34816
	ds_read_b128 v[204:207], v144 offset:35840
	ds_read_b128 v[208:211], v144 offset:36864
	ds_read_b128 v[212:215], v144 offset:37888
	ds_read_b128 v[216:219], v144 offset:38912
	ds_read_b128 v[220:223], v144 offset:39936
	global_load_lds_dwordx4 v232, s[16:17]
	s_mov_b32 m0, s33
	s_nop 0
	global_load_lds_dwordx4 v233, s[16:17]
	s_waitcnt lgkmcnt(8)
	s_barrier
	s_waitcnt lgkmcnt(0)
	s_waitcnt lgkmcnt(0)
	v_mfma_f32_16x16x32_bf16 v[126:129], v[164:167], v[180:183], v[126:129]
	v_mfma_f32_16x16x32_bf16 v[122:125], v[172:175], v[180:183], v[122:125]
	v_mfma_f32_16x16x32_bf16 v[118:121], v[164:167], v[200:203], v[118:121]
	v_mfma_f32_16x16x32_bf16 v[114:117], v[172:175], v[200:203], v[114:117]
	v_mfma_f32_16x16x32_bf16 v[110:113], v[164:167], v[208:211], v[110:113]
	v_mfma_f32_16x16x32_bf16 v[106:109], v[172:175], v[208:211], v[106:109]
	v_mfma_f32_16x16x32_bf16 v[102:105], v[164:167], v[216:219], v[102:105]
	v_mfma_f32_16x16x32_bf16 v[98:101], v[172:175], v[216:219], v[98:101]
	v_mfma_f32_16x16x32_bf16 v[126:129], v[168:171], v[196:199], v[126:129]
	v_mfma_f32_16x16x32_bf16 v[122:125], v[176:179], v[196:199], v[122:125]
	v_mfma_f32_16x16x32_bf16 v[118:121], v[168:171], v[204:207], v[118:121]
	v_mfma_f32_16x16x32_bf16 v[114:117], v[176:179], v[204:207], v[114:117]
	v_mfma_f32_16x16x32_bf16 v[110:113], v[168:171], v[212:215], v[110:113]
	v_mfma_f32_16x16x32_bf16 v[106:109], v[176:179], v[212:215], v[106:109]
	v_mfma_f32_16x16x32_bf16 v[102:105], v[168:171], v[220:223], v[102:105]
	v_mfma_f32_16x16x32_bf16 v[98:101], v[176:179], v[220:223], v[98:101]
	s_barrier
	s_mov_b32 m0, s35
	v_or_b32_e32 v159, 0x1c000, v143
	v_add_u32_e32 v161, 0x1c100, v143
	v_add_u32_e32 v163, 0x180, v240
	v_add_u32_e32 v160, 0x1c400, v143
	ds_read_b128 v[224:227], v159
	ds_read_b128 v[228:231], v160
	v_add_u32_e32 v162, 0x1c500, v143
	ds_read_b128 v[232:235], v161
	ds_read_b128 v[236:239], v162
	global_load_lds_dwordx4 v163, s[8:9]
	v_add_u32_e32 v240, 0x180, v241
	s_mov_b32 m0, s93
	s_nop 0
	global_load_lds_dwordx4 v240, s[8:9]
	s_barrier
; #define WAIT_V(n) asm volatile("s_waitcnt vmcnt(%0)" ::"n"(n) : "memory")
; #define WAIT_L(n) asm volatile("s_waitcnt lgkmcnt(%0)" ::"n"(n) : "memory")
; #define SBAR() __builtin_amdgcn_sched_barrier(0)
; #define STAGE(P, base, kt) do { _Pragma("unroll") for (int _i = 0; _i < 2; ++_i)                                        \
;       __builtin_amdgcn_global_load_lds((const unsigned*)((base) + (size_t)(sOff[_i] + (unsigned)(kt) * (BK * 2))),        \
;                                        (unsigned*)((P) + wid * 1024 + _i * 8192), 16, 0, 0); } while (0)
; #define BAR __builtin_amdgcn_s_barrier()
; template <int EPI, int N, int K>
; __device__ __forceinline__ void phase_gemm(const Params& p, const u16* __restrict__ A, const u16* __restrict__ Bt, int nM, char* shm,
;                            u16* __restrict__ outp, float* __restrict__ rowss) {
;     ...
;       BAR; WAIT_L(0); MMA(1, 0, At, B0); BAR; SBAR();
;       STAGE(SB(1, 1), B1p, t + 3);
;       WAIT_V(6); BAR; MMA(1, 1, At, B1); BAR;
;     }
	s_waitcnt lgkmcnt(0)
	s_waitcnt lgkmcnt(0)
	v_mfma_f32_16x16x32_bf16 v[92:95], v[224:227], v[180:183], v[92:95]
	v_mfma_f32_16x16x32_bf16 v[88:91], v[232:235], v[180:183], v[88:91]
	v_mfma_f32_16x16x32_bf16 v[84:87], v[224:227], v[200:203], v[84:87]
	v_mfma_f32_16x16x32_bf16 v[80:83], v[232:235], v[200:203], v[80:83]
	v_mfma_f32_16x16x32_bf16 v[76:79], v[224:227], v[208:211], v[76:79]
	v_mfma_f32_16x16x32_bf16 v[72:75], v[232:235], v[208:211], v[72:75]
	v_mfma_f32_16x16x32_bf16 v[68:71], v[224:227], v[216:219], v[68:71]
	v_mfma_f32_16x16x32_bf16 v[64:67], v[232:235], v[216:219], v[64:67]
	v_mfma_f32_16x16x32_bf16 v[92:95], v[228:231], v[196:199], v[92:95]
	v_mfma_f32_16x16x32_bf16 v[88:91], v[236:239], v[196:199], v[88:91]
	v_mfma_f32_16x16x32_bf16 v[84:87], v[228:231], v[204:207], v[84:87]
	v_mfma_f32_16x16x32_bf16 v[80:83], v[236:239], v[204:207], v[80:83]
	v_mfma_f32_16x16x32_bf16 v[76:79], v[228:231], v[212:215], v[76:79]
	v_mfma_f32_16x16x32_bf16 v[72:75], v[236:239], v[212:215], v[72:75]
	v_mfma_f32_16x16x32_bf16 v[68:71], v[228:231], v[220:223], v[68:71]
	v_mfma_f32_16x16x32_bf16 v[64:67], v[236:239], v[220:223], v[64:67]
	s_mov_b32 m0, s24
	s_barrier
	ds_read_b128 v[180:183], v144 offset:49152
	ds_read_b128 v[196:199], v144 offset:50176
	ds_read_b128 v[200:203], v144 offset:51200
	ds_read_b128 v[204:207], v144 offset:52224
	ds_read_b128 v[208:211], v144 offset:53248
	ds_read_b128 v[212:215], v144 offset:54272
	ds_read_b128 v[216:219], v144 offset:55296
	ds_read_b128 v[220:223], v144 offset:56320
	global_load_lds_dwordx4 v163, s[10:11]
	s_mov_b32 m0, s25
	s_nop 0
	global_load_lds_dwordx4 v240, s[10:11]
	s_barrier
	s_waitcnt lgkmcnt(0)
	s_waitcnt lgkmcnt(0)
	v_mfma_f32_16x16x32_bf16 v[60:63], v[164:167], v[180:183], v[60:63]
	v_mfma_f32_16x16x32_bf16 v[56:59], v[172:175], v[180:183], v[56:59]
	v_mfma_f32_16x16x32_bf16 v[52:55], v[164:167], v[200:203], v[52:55]
	v_mfma_f32_16x16x32_bf16 v[48:51], v[172:175], v[200:203], v[48:51]
	v_mfma_f32_16x16x32_bf16 v[44:47], v[164:167], v[208:211], v[44:47]
	v_mfma_f32_16x16x32_bf16 v[40:43], v[172:175], v[208:211], v[40:43]
	v_mfma_f32_16x16x32_bf16 v[36:39], v[164:167], v[216:219], v[36:39]
	v_mfma_f32_16x16x32_bf16 v[32:35], v[172:175], v[216:219], v[32:35]
	v_mfma_f32_16x16x32_bf16 v[60:63], v[168:171], v[196:199], v[60:63]
	v_mfma_f32_16x16x32_bf16 v[56:59], v[176:179], v[196:199], v[56:59]
	v_mfma_f32_16x16x32_bf16 v[52:55], v[168:171], v[204:207], v[52:55]
	v_mfma_f32_16x16x32_bf16 v[48:51], v[176:179], v[204:207], v[48:51]
	v_mfma_f32_16x16x32_bf16 v[44:47], v[168:171], v[212:215], v[44:47]
	v_mfma_f32_16x16x32_bf16 v[40:43], v[176:179], v[212:215], v[40:43]
	v_mfma_f32_16x16x32_bf16 v[36:39], v[168:171], v[220:223], v[36:39]
	v_mfma_f32_16x16x32_bf16 v[32:35], v[176:179], v[220:223], v[32:35]
	s_barrier
	s_mov_b32 m0, s26
	s_nop 0
	global_load_lds_dwordx4 v163, s[18:19]
	s_mov_b32 m0, s27
	s_nop 0
	global_load_lds_dwordx4 v240, s[18:19]
	s_waitcnt vmcnt(6)
	s_barrier
	v_mfma_f32_16x16x32_bf16 v[28:31], v[224:227], v[180:183], v[28:31]
	v_mfma_f32_16x16x32_bf16 v[24:27], v[232:235], v[180:183], v[24:27]
	v_mfma_f32_16x16x32_bf16 v[20:23], v[224:227], v[200:203], v[20:23]
	v_mfma_f32_16x16x32_bf16 v[16:19], v[232:235], v[200:203], v[16:19]
	v_mfma_f32_16x16x32_bf16 v[12:15], v[224:227], v[208:211], v[12:15]
	v_mfma_f32_16x16x32_bf16 v[8:11], v[232:235], v[208:211], v[8:11]
	v_mfma_f32_16x16x32_bf16 v[4:7], v[224:227], v[216:219], v[4:7]
	v_mfma_f32_16x16x32_bf16 v[0:3], v[232:235], v[216:219], v[0:3]
	v_mfma_f32_16x16x32_bf16 v[28:31], v[228:231], v[196:199], v[28:31]
	v_mfma_f32_16x16x32_bf16 v[24:27], v[236:239], v[196:199], v[24:27]
	v_mfma_f32_16x16x32_bf16 v[20:23], v[228:231], v[204:207], v[20:23]
	v_mfma_f32_16x16x32_bf16 v[16:19], v[236:239], v[204:207], v[16:19]
	v_mfma_f32_16x16x32_bf16 v[12:15], v[228:231], v[212:215], v[12:15]
	v_mfma_f32_16x16x32_bf16 v[8:11], v[236:239], v[212:215], v[8:11]
	v_mfma_f32_16x16x32_bf16 v[4:7], v[228:231], v[220:223], v[4:7]
	v_mfma_f32_16x16x32_bf16 v[0:3], v[236:239], v[220:223], v[0:3]
	s_add_i32 s53, s53, 2
	v_add_u32_e32 v141, 0x100, v141
	s_cmp_lt_u32 s53, 12
	v_add_u32_e32 v140, 0x100, v140
	s_barrier

; __device__ __forceinline__ int nblk_opaque() { int t = gridDim.x; asm volatile("" : "+s"(t)); return t; }
; __device__ __forceinline__ int tid_opaque() { int t = threadIdx.x; asm volatile("" : "+v"(t)); return t; }
; template <typename T> __device__ __forceinline__ T* launder(T* p) { asm volatile("" : "+s"(p)); return p; }
; #define STAGE(P, base, kt) do { _Pragma("unroll") for (int _i = 0; _i < 2; ++_i)                                        \
;       __builtin_amdgcn_global_load_lds((const unsigned*)((base) + (size_t)(sOff[_i] + (unsigned)(kt) * (BK * 2))),        \
;                                        (unsigned*)((P) + wid * 1024 + _i * 8192), 16, 0, 0); } while (0)
; #define TILE_BASES(pm_, pn_, a0_, b0_) do {                                                                          \
;     const char* ta_ = (const char*)(A + (size_t)(pm_) * 256 * K); const char* tb_ = (const char*)(Bt + (size_t)(pn_) * 256 * K); \
;     if (EPI == EPI_QKV_A && (pn_) >= 8) { a0_ = tb_; b0_ = ta_; } else { a0_ = ta_; b0_ = tb_; } } while (0)
; template <int EPI, int N, int K>
; __device__ __forceinline__ void phase_gemm(const Params& p, const u16* __restrict__ A, const u16* __restrict__ Bt, int nM, char* shm,
;                            u16* __restrict__ outp, float* __restrict__ rowss) {
;     ...
;   const int tid = tid_opaque(), wid = __builtin_amdgcn_readfirstlane(tid >> 6), lane = tid & 63, wr = wid >> 2, wc = wid & 3, fr = lane & 15, fq = lane >> 4;
;   A = launder(A); Bt = launder(Bt); outp = launder(outp); rowss = launder(rowss);
;   unsigned sOff[2];
; #pragma unroll
;   for (int i = 0; i < 2; ++i) { int R_, C_; stage_rc<2>(wid * 1024 + i * 8192 + lane * 16, R_, C_); sOff[i] = (unsigned)(R_ * K + C_) * 2u; }
;   const int laneoff = (fr * 64 + fq * 16) ^ ((fr >> 3) << 5);
;   const int aoff = wr * 8192 + laneoff;
;   const int boff = wc * 4096 + (fr >> 3) * 2048 + ((512 * ((fr >> 2) & 1) + 64 * (fr & 3) + fq * 16) ^ (((fr >> 2) & 1) << 5));
;   const int nbg = nblk_opaque();
;     ...
;   int v = blockIdx.x;
;   if (v >= nwg) return;
;   int pm, pn;
;   TILE_COORDS(v, pm, pn);
;   const char *A0, *B0p;
;   TILE_BASES(pm, pn, A0, B0p);
;   STAGE(SB(0, 0), B0p, 0); STAGE(SA(0, 0), A0, 0); STAGE(SB(0, 1), B0p + (size_t)128 * K * 2, 0); STAGE(SA(0, 1), A0 + (size_t)128 * K * 2, 0);
;   STAGE(SB(1, 0), B0p, 1); STAGE(SA(1, 0), A0, 1); STAGE(SB(1, 1), B0p + (size_t)128 * K * 2, 1);
.LBB0_547:
	v_readlane_b32 s52, v253, 22
	v_readlane_b32 s62, v253, 32
	v_readlane_b32 s63, v253, 33
	v_readlane_b32 s64, v253, 34
	v_readlane_b32 s65, v253, 35
	v_mov_b32_e32 v0, v184
	s_mov_b64 s[2:3], s[62:63]
	s_mov_b64 s[4:5], s[64:65]
	s_mov_b64 s[6:7], 0
	v_readlane_b32 s18, v253, 1
	v_readlane_b32 s6, v253, 61
	v_readlane_b32 s7, v253, 62
	v_readfirstlane_b32 s14, v0
	s_andn2_b64 vcc, exec, s[6:7]
	v_readlane_b32 s53, v253, 23
	v_readlane_b32 s54, v253, 24
	v_readlane_b32 s55, v253, 25
	v_readlane_b32 s56, v253, 26
	v_readlane_b32 s57, v253, 27
	v_readlane_b32 s58, v253, 28
	v_readlane_b32 s59, v253, 29
	v_readlane_b32 s60, v253, 30
	v_readlane_b32 s61, v253, 31
	v_readlane_b32 s66, v253, 36
	v_readlane_b32 s67, v253, 37
	s_cbranch_vccnz .LBB0_559
	s_ashr_i32 s6, s14, 6
	s_waitcnt lgkmcnt(0)
	v_lshlrev_b32_e32 v1, 4, v0
	v_and_b32_e32 v2, 32, v0
	v_lshlrev_b32_e32 v4, 9, v0
	s_lshr_b32 s7, s14, 31
	s_lshl_b32 s19, s6, 10
	v_bitop3_b32 v3, v1, v2, 48 bitop3:0x6c
	v_and_b32_e32 v142, 0x7800, v4
	s_add_i32 s7, s6, s7
	v_or_b32_e32 v3, v3, v142
	s_ashr_i32 s15, s7, 1
	s_and_b32 s7, s7, 0x3fffffe
	s_add_i32 s22, s19, 0x2000
	s_sub_i32 s7, s6, s7
	v_lshl_or_b32 v4, s15, 15, v3
	s_ashr_i32 s16, s22, 10
	v_lshl_add_u32 v96, s7, 6, v4
	s_lshr_b32 s7, s16, 31
	s_add_i32 s7, s16, s7
	s_ashr_i32 s17, s7, 1
	s_and_b32 s7, s7, 0x3fffffe
	s_sub_i32 s7, s16, s7
	v_lshl_or_b32 v3, s17, 15, v3
	s_and_b32 s29, s6, 3
	s_ashr_i32 s30, s14, 8
	v_lshl_add_u32 v130, s7, 6, v3
	s_lshl_b32 s28, s29, 12
	s_lshl_b32 s31, s30, 13
	v_readlane_b32 s6, v254, 3
	v_readlane_b32 s7, v254, 4
	s_add_u32 s6, s0, s6
	s_mov_b64 s[60:61], s[92:93]
	s_addc_u32 s7, s1, s7
	s_add_i32 s23, s19, 0x10000
	s_add_i32 s92, s19, 0x12000
	v_readlane_b32 s8, v254, 1
	s_mov_b32 m0, s23
	v_readlane_b32 s9, v254, 2
	s_add_u32 s8, s2, s8
	global_load_lds_dwordx4 v96, s[6:7]
	s_mov_b32 m0, s92
	s_addc_u32 s9, s3, s9
	global_load_lds_dwordx4 v130, s[6:7]
	s_mov_b32 m0, s19
	s_add_u32 s10, s6, 0x40000
	global_load_lds_dwordx4 v96, s[8:9]
	s_mov_b32 m0, s22
	s_addc_u32 s11, s7, 0
	s_add_i32 s94, s19, 0x14000
	s_add_i32 s95, s19, 0x16000
	global_load_lds_dwordx4 v130, s[8:9]
	s_mov_b32 m0, s94
	s_add_u32 s12, s8, 0x40000
	global_load_lds_dwordx4 v96, s[10:11]
	s_mov_b32 m0, s95
	s_addc_u32 s13, s9, 0
	s_add_i32 s96, s19, 0x4000
	global_load_lds_dwordx4 v130, s[10:11]
	s_mov_b32 m0, s96
	s_add_i32 s33, s19, 0x6000
	global_load_lds_dwordx4 v96, s[12:13]
	s_mov_b32 m0, s33
	s_add_i32 s35, s19, 0x18000
	global_load_lds_dwordx4 v130, s[12:13]
	v_add_u32_e32 v132, 0x80, v96
	s_mov_b32 m0, s35
	s_add_i32 s93, s19, 0x1a000
	global_load_lds_dwordx4 v132, s[6:7]
	v_add_u32_e32 v134, 0x80, v130
	s_mov_b32 m0, s93
	s_add_i32 s24, s19, 0x8000
	s_mov_b32 s59, s25
	global_load_lds_dwordx4 v134, s[6:7]
	s_mov_b32 m0, s24
	s_add_i32 s25, s19, 0xa000
	global_load_lds_dwordx4 v132, s[8:9]
	s_mov_b32 m0, s25
	s_add_i32 s26, s19, 0x1c000
	global_load_lds_dwordx4 v134, s[8:9]
	s_mov_b32 m0, s26
	s_add_i32 s27, s19, 0x1e000
	global_load_lds_dwordx4 v132, s[10:11]
	s_mov_b32 m0, s27
	v_lshlrev_b32_e32 v4, 6, v0
	global_load_lds_dwordx4 v134, s[10:11]
	v_bfe_u32 v3, v0, 2, 1
	v_and_b32_e32 v4, 0xc0, v4
	s_cmp_eq_u32 s30, 1
	v_lshl_or_b32 v4, v3, 9, v4
	v_and_b32_e32 v5, 48, v0
	v_lshlrev_b32_e32 v3, 5, v3
	s_cselect_b64 s[10:11], -1, 0
	s_cmpk_lt_u32 s14, 0x100
	v_bitop3_b32 v3, v4, v3, v5 bitop3:0x36
	v_and_b32_e32 v4, 15, v0
	v_bfe_u32 v0, v0, 3, 1
	s_cselect_b64 s[12:13], -1, 0
	s_mulk_i32 s15, 0x7f80
	s_andn2_b32 s14, s14, 63
	v_and_b32_e32 v1, 48, v1
	v_lshlrev_b32_e32 v6, 11, v0
	s_mulk_i32 s17, 0x7f80
	s_lshl_b32 s16, s16, 6
	s_add_i32 s14, s14, s15
	v_or3_b32 v143, s28, v6, v3
	v_lshl_or_b32 v3, v4, 6, v5
	v_lshlrev_b32_e32 v0, 5, v0
	s_add_i32 s16, s16, s17
	v_bitop3_b32 v146, s14, v1, v2 bitop3:0xf6
	v_readlane_b32 s14, v253, 63
	v_bitop3_b32 v144, v3, s31, v0 bitop3:0xde
	v_mov_b32_e32 v131, v97
	v_mov_b32_e32 v133, v97
	v_mov_b32_e32 v135, v97
	s_lshl_b32 s28, s30, 6
	s_lshl_b32 s29, s29, 5
	v_add_u32_e32 v136, 0x780, v96
	v_mov_b32_e32 v137, v97
	v_add_u32_e32 v138, 0x780, v130
	v_mov_b32_e32 v139, v97
	v_bitop3_b32 v145, s16, v1, v2 bitop3:0xf6
	v_readlane_b32 s31, v254, 5
	s_mov_b32 s52, s14
	v_readlane_b32 s30, v253, 0
	s_movk_i32 s58, 0x421
	s_movk_i32 s62, 0xb00
	s_mov_b32 s63, 0x16000
	s_mov_b32 s64, 0x2c000
	s_mov_b32 s65, 0x42000
	s_mov_b32 s66, 0xb0000
	s_mov_b32 s67, 0xc6000
	s_mov_b32 s69, 0xdc000
	v_readlane_b32 s15, v254, 0
	s_waitcnt vmcnt(0)
	s_branch .LBB0_550
; #define SBAR() __builtin_amdgcn_sched_barrier(0)
; template <int EPI, int N, int K>
; __device__ __forceinline__ void phase_gemm(const Params& p, const u16* __restrict__ A, const u16* __restrict__ Bt, int nM, char* shm,
;                            u16* __restrict__ outp, float* __restrict__ rowss) {
;     ...
;     if constexpr (EPI == EPI_SWIGLU) {
;       u16* ob = outp + (size_t)((unsigned)(brow + wr * 64 + fr) * DFF + (unsigned)(pn * 128 + wc * 32 + fq * 8));
; #pragma unroll
;       for (int ai = 0; ai < 2; ++ai)
; #pragma unroll
;         for (int m = 0; m < 4; ++m) {
;           float hv[8];
; #pragma unroll
;           for (int n = 0; n < 2; ++n)
; #pragma unroll
;             for (int j = 0; j < 4; ++j) {
;               float g = acc[ai][0][m][n][j], u = acc[ai][1][m][n][j];
;               hv[n * 4 + j] = g * u * __builtin_amdgcn_rcpf(1.f + __builtin_amdgcn_exp2f(-1.4426950408889634f * g));
;             }
;           u32x4 w = {cvtpk(hv[0], hv[1]), cvtpk(hv[2], hv[3]), cvtpk(hv[4], hv[5]), cvtpk(hv[6], hv[7])};
;           *(u32x4*)(ob + (ai * 128 + m * 16) * DFF) = w;
;           SBAR();
;         }
.LBB0_549:
	v_mul_f32_e32 v118, v114, v118
	v_mul_f32_e32 v114, 0xbfb8aa3b, v114
	v_mul_f32_e32 v126, v122, v126
	v_mul_f32_e32 v122, 0xbfb8aa3b, v122
	v_exp_f32_e32 v114, v114
	v_exp_f32_e32 v122, v122
	s_lshl_b32 s52, s52, 8
	v_mov_b32_e32 v140, v184
	v_add_f32_e32 v114, 1.0, v114
	v_add_f32_e32 v122, 1.0, v122
	v_rcp_f32_e32 v114, v114
	v_rcp_f32_e32 v122, v122
	s_add_i32 s52, s52, s28
	v_mul_f32_e32 v118, v114, v118
	v_mul_f32_e32 v114, v115, v119
	v_mul_f32_e32 v115, 0xbfb8aa3b, v115
	v_mul_f32_e32 v122, v122, v126
	v_mul_f32_e32 v126, v123, v127
	v_mul_f32_e32 v123, 0xbfb8aa3b, v123
	v_exp_f32_e32 v115, v115
	v_exp_f32_e32 v123, v123
	s_lshl_b32 s31, s31, 7
	v_and_or_b32 v141, v140, 15, s52
	v_add_f32_e32 v115, 1.0, v115
	v_add_f32_e32 v123, 1.0, v123
	v_rcp_f32_e32 v115, v115
	v_rcp_f32_e32 v123, v123
	s_or_b32 s31, s31, s29
	v_lshrrev_b32_e32 v140, 1, v140
	v_mul_f32_e32 v119, v115, v114
	v_mul_f32_e32 v115, 0xbfb8aa3b, v116
	v_mul_f32_e32 v123, v123, v126
	v_mul_f32_e32 v126, v124, v128
	v_mul_f32_e32 v124, 0xbfb8aa3b, v124
	v_exp_f32_e32 v115, v115
	v_exp_f32_e32 v124, v124
	v_mul_f32_e32 v114, v116, v120
	v_and_or_b32 v140, v140, 24, s31
	v_add_f32_e32 v115, 1.0, v115
	v_add_f32_e32 v124, 1.0, v124
	v_rcp_f32_e32 v115, v115
	v_rcp_f32_e32 v124, v124
	v_mad_u64_u32 v[140:141], s[52:53], v141, s62, v[140:141]
	v_mul_f32_e32 v120, v115, v114
	v_mul_f32_e32 v115, 0xbfb8aa3b, v117
	v_mul_f32_e32 v124, v124, v126
	v_mul_f32_e32 v126, v125, v129
	v_mul_f32_e32 v125, 0xbfb8aa3b, v125
	v_exp_f32_e32 v115, v115
	v_exp_f32_e32 v125, v125
	v_mov_b32_e32 v141, v97
	v_mul_f32_e32 v114, v117, v121
	v_add_f32_e32 v115, 1.0, v115
	v_add_f32_e32 v125, 1.0, v125
	v_rcp_f32_e32 v115, v115
	v_rcp_f32_e32 v125, v125
	v_lshl_add_u64 v[140:141], v[140:141], 1, s[4:5]
	v_mul_f32_e32 v117, v115, v114
	v_mul_f32_e32 v125, v125, v126
	v_cvt_pk_bf16_f32 v114, v122, v123
	v_cvt_pk_bf16_f32 v115, v124, v125
	v_cvt_pk_bf16_f32 v116, v118, v119
	v_cvt_pk_bf16_f32 v117, v120, v117
	global_store_dwordx4 v[140:141], v[114:117], off
	v_mul_f32_e32 v110, v106, v110
	v_mul_f32_e32 v106, 0xbfb8aa3b, v106
	v_mul_f32_e32 v102, v98, v102
	v_mul_f32_e32 v98, 0xbfb8aa3b, v98
	v_exp_f32_e32 v106, v106
	v_exp_f32_e32 v98, v98
	v_add_f32_e32 v106, 1.0, v106
	v_add_f32_e32 v98, 1.0, v98
	v_rcp_f32_e32 v106, v106
	v_rcp_f32_e32 v98, v98
	v_mul_f32_e32 v106, v106, v110
	v_mul_f32_e32 v110, v107, v111
	v_mul_f32_e32 v107, 0xbfb8aa3b, v107
	v_mul_f32_e32 v102, v98, v102
	v_mul_f32_e32 v98, v99, v103
	v_mul_f32_e32 v99, 0xbfb8aa3b, v99
	v_exp_f32_e32 v107, v107
	v_exp_f32_e32 v99, v99
	v_add_f32_e32 v107, 1.0, v107
	v_add_f32_e32 v99, 1.0, v99
	v_rcp_f32_e32 v107, v107
	v_rcp_f32_e32 v99, v99
	v_mul_f32_e32 v107, v107, v110
	v_mul_f32_e32 v110, v108, v112
	v_mul_f32_e32 v108, 0xbfb8aa3b, v108
	v_mul_f32_e32 v103, v99, v98
	v_mul_f32_e32 v99, 0xbfb8aa3b, v100
	v_exp_f32_e32 v108, v108
	v_exp_f32_e32 v99, v99
	v_mul_f32_e32 v98, v100, v104
	v_add_f32_e32 v108, 1.0, v108
	v_add_f32_e32 v99, 1.0, v99
	v_rcp_f32_e32 v108, v108
	v_rcp_f32_e32 v99, v99
	v_mul_f32_e32 v108, v108, v110
	v_mul_f32_e32 v110, v109, v113
	v_mul_f32_e32 v109, 0xbfb8aa3b, v109
	v_mul_f32_e32 v104, v99, v98
	v_mul_f32_e32 v99, 0xbfb8aa3b, v101
	v_exp_f32_e32 v109, v109
	v_exp_f32_e32 v99, v99
	v_mul_f32_e32 v98, v101, v105
	v_add_f32_e32 v109, 1.0, v109
	v_add_f32_e32 v99, 1.0, v99
	v_rcp_f32_e32 v109, v109
	v_rcp_f32_e32 v99, v99
	v_mul_f32_e32 v109, v109, v110
	v_mul_f32_e32 v101, v99, v98
	v_cvt_pk_bf16_f32 v98, v106, v107
	v_cvt_pk_bf16_f32 v99, v108, v109
	v_cvt_pk_bf16_f32 v100, v102, v103
	v_add_co_u32_e32 v102, vcc, s63, v140
	v_cvt_pk_bf16_f32 v101, v104, v101
	s_nop 1
	v_addc_co_u32_e32 v103, vcc, 0, v141, vcc
	global_store_dwordx4 v[102:103], v[98:101], off
	v_mul_f32_e32 v92, v88, v92
	v_mul_f32_e32 v88, 0xbfb8aa3b, v88
	v_mul_f32_e32 v84, v80, v84
	v_mul_f32_e32 v80, 0xbfb8aa3b, v80
	v_exp_f32_e32 v88, v88
	v_exp_f32_e32 v80, v80
	v_add_f32_e32 v88, 1.0, v88
	v_add_f32_e32 v80, 1.0, v80
	v_rcp_f32_e32 v88, v88
	v_rcp_f32_e32 v80, v80
	v_mul_f32_e32 v88, v88, v92
	v_mul_f32_e32 v92, v89, v93
	v_mul_f32_e32 v89, 0xbfb8aa3b, v89
	v_mul_f32_e32 v84, v80, v84
	v_mul_f32_e32 v80, v81, v85
	v_mul_f32_e32 v81, 0xbfb8aa3b, v81
	v_exp_f32_e32 v89, v89
	v_exp_f32_e32 v81, v81
	v_add_f32_e32 v89, 1.0, v89
	v_add_f32_e32 v81, 1.0, v81
	v_rcp_f32_e32 v89, v89
	v_rcp_f32_e32 v81, v81
	v_mul_f32_e32 v89, v89, v92
	v_mul_f32_e32 v92, v90, v94
	v_mul_f32_e32 v90, 0xbfb8aa3b, v90
	v_mul_f32_e32 v85, v81, v80
	v_mul_f32_e32 v81, 0xbfb8aa3b, v82
	v_exp_f32_e32 v90, v90
	v_exp_f32_e32 v81, v81
	v_mul_f32_e32 v80, v82, v86
	v_add_f32_e32 v90, 1.0, v90
	v_add_f32_e32 v81, 1.0, v81
	v_rcp_f32_e32 v90, v90
	v_rcp_f32_e32 v81, v81
	v_mul_f32_e32 v90, v90, v92
	v_mul_f32_e32 v92, v91, v95
	v_mul_f32_e32 v91, 0xbfb8aa3b, v91
	v_mul_f32_e32 v86, v81, v80
	v_mul_f32_e32 v81, 0xbfb8aa3b, v83
	v_exp_f32_e32 v91, v91
	v_exp_f32_e32 v81, v81
	v_mul_f32_e32 v80, v83, v87
	v_add_f32_e32 v91, 1.0, v91
	v_add_f32_e32 v81, 1.0, v81
	v_rcp_f32_e32 v91, v91
	v_rcp_f32_e32 v81, v81
	v_mul_f32_e32 v91, v91, v92
	v_mul_f32_e32 v83, v81, v80
	v_cvt_pk_bf16_f32 v80, v88, v89
	v_cvt_pk_bf16_f32 v81, v90, v91
	v_cvt_pk_bf16_f32 v82, v84, v85
	v_add_co_u32_e32 v84, vcc, s64, v140
	v_cvt_pk_bf16_f32 v83, v86, v83
	s_nop 1
	v_addc_co_u32_e32 v85, vcc, 0, v141, vcc
	global_store_dwordx4 v[84:85], v[80:83], off
	v_mul_f32_e32 v76, v72, v76
	v_mul_f32_e32 v72, 0xbfb8aa3b, v72
	v_mul_f32_e32 v68, v64, v68
	v_mul_f32_e32 v64, 0xbfb8aa3b, v64
	v_exp_f32_e32 v72, v72
	v_exp_f32_e32 v64, v64
	v_add_f32_e32 v72, 1.0, v72
	v_add_f32_e32 v64, 1.0, v64
; #define SBAR() __builtin_amdgcn_sched_barrier(0)
; template <int EPI, int N, int K>
; __device__ __forceinline__ void phase_gemm(const Params& p, const u16* __restrict__ A, const u16* __restrict__ Bt, int nM, char* shm,
;                            u16* __restrict__ outp, float* __restrict__ rowss) {
;     ...
;     if constexpr (EPI == EPI_SWIGLU) {
;       u16* ob = outp + (size_t)((unsigned)(brow + wr * 64 + fr) * DFF + (unsigned)(pn * 128 + wc * 32 + fq * 8));
; #pragma unroll
;       for (int ai = 0; ai < 2; ++ai)
; #pragma unroll
;         for (int m = 0; m < 4; ++m) {
;           float hv[8];
; #pragma unroll
;           for (int n = 0; n < 2; ++n)
; #pragma unroll
;             for (int j = 0; j < 4; ++j) {
;               float g = acc[ai][0][m][n][j], u = acc[ai][1][m][n][j];
;               hv[n * 4 + j] = g * u * __builtin_amdgcn_rcpf(1.f + __builtin_amdgcn_exp2f(-1.4426950408889634f * g));
;             }
;           u32x4 w = {cvtpk(hv[0], hv[1]), cvtpk(hv[2], hv[3]), cvtpk(hv[4], hv[5]), cvtpk(hv[6], hv[7])};
;           *(u32x4*)(ob + (ai * 128 + m * 16) * DFF) = w;
;           SBAR();
;         }
	v_rcp_f32_e32 v72, v72
	v_rcp_f32_e32 v64, v64
	v_mul_f32_e32 v72, v72, v76
	v_mul_f32_e32 v76, v73, v77
	v_mul_f32_e32 v73, 0xbfb8aa3b, v73
	v_mul_f32_e32 v68, v64, v68
	v_mul_f32_e32 v64, v65, v69
	v_mul_f32_e32 v65, 0xbfb8aa3b, v65
	v_exp_f32_e32 v73, v73
	v_exp_f32_e32 v65, v65
	v_add_f32_e32 v73, 1.0, v73
	v_add_f32_e32 v65, 1.0, v65
	v_rcp_f32_e32 v73, v73
	v_rcp_f32_e32 v65, v65
	v_mul_f32_e32 v73, v73, v76
	v_mul_f32_e32 v76, v74, v78
	v_mul_f32_e32 v74, 0xbfb8aa3b, v74
	v_mul_f32_e32 v69, v65, v64
	v_mul_f32_e32 v65, 0xbfb8aa3b, v66
	v_exp_f32_e32 v74, v74
	v_exp_f32_e32 v65, v65
	v_mul_f32_e32 v64, v66, v70
	v_add_f32_e32 v74, 1.0, v74
	v_add_f32_e32 v65, 1.0, v65
	v_rcp_f32_e32 v74, v74
	v_rcp_f32_e32 v65, v65
	v_mul_f32_e32 v74, v74, v76
	v_mul_f32_e32 v76, v75, v79
	v_mul_f32_e32 v75, 0xbfb8aa3b, v75
	v_mul_f32_e32 v70, v65, v64
	v_mul_f32_e32 v65, 0xbfb8aa3b, v67
	v_exp_f32_e32 v75, v75
	v_exp_f32_e32 v65, v65
	v_mul_f32_e32 v64, v67, v71
	v_add_f32_e32 v75, 1.0, v75
	v_add_f32_e32 v65, 1.0, v65
	v_rcp_f32_e32 v75, v75
	v_rcp_f32_e32 v65, v65
	v_mul_f32_e32 v75, v75, v76
	v_mul_f32_e32 v67, v65, v64
	v_cvt_pk_bf16_f32 v64, v72, v73
	v_cvt_pk_bf16_f32 v65, v74, v75
	v_cvt_pk_bf16_f32 v66, v68, v69
	v_add_co_u32_e32 v68, vcc, s65, v140
	v_cvt_pk_bf16_f32 v67, v70, v67
	s_nop 1
	v_addc_co_u32_e32 v69, vcc, 0, v141, vcc
	global_store_dwordx4 v[68:69], v[64:67], off
	v_mul_f32_e32 v60, v56, v60
	v_mul_f32_e32 v56, 0xbfb8aa3b, v56
	v_mul_f32_e32 v52, v48, v52
	v_mul_f32_e32 v48, 0xbfb8aa3b, v48
	v_exp_f32_e32 v56, v56
	v_exp_f32_e32 v48, v48
	v_add_f32_e32 v56, 1.0, v56
	v_add_f32_e32 v48, 1.0, v48
	v_rcp_f32_e32 v56, v56
	v_rcp_f32_e32 v48, v48
	v_mul_f32_e32 v56, v56, v60
	v_mul_f32_e32 v60, v57, v61
	v_mul_f32_e32 v57, 0xbfb8aa3b, v57
	v_mul_f32_e32 v52, v48, v52
	v_mul_f32_e32 v48, v49, v53
	v_mul_f32_e32 v49, 0xbfb8aa3b, v49
	v_exp_f32_e32 v57, v57
	v_exp_f32_e32 v49, v49
	v_add_f32_e32 v57, 1.0, v57
	v_add_f32_e32 v49, 1.0, v49
	v_rcp_f32_e32 v57, v57
	v_rcp_f32_e32 v49, v49
	v_mul_f32_e32 v57, v57, v60
	v_mul_f32_e32 v60, v58, v62
	v_mul_f32_e32 v58, 0xbfb8aa3b, v58
	v_mul_f32_e32 v53, v49, v48
	v_mul_f32_e32 v49, 0xbfb8aa3b, v50
	v_exp_f32_e32 v58, v58
	v_exp_f32_e32 v49, v49
	v_mul_f32_e32 v48, v50, v54
	v_add_f32_e32 v58, 1.0, v58
	v_add_f32_e32 v49, 1.0, v49
	v_rcp_f32_e32 v58, v58
	v_rcp_f32_e32 v49, v49
	v_mul_f32_e32 v58, v58, v60
	v_mul_f32_e32 v60, v59, v63
	v_mul_f32_e32 v59, 0xbfb8aa3b, v59
	v_mul_f32_e32 v54, v49, v48
	v_mul_f32_e32 v49, 0xbfb8aa3b, v51
	v_exp_f32_e32 v59, v59
	v_exp_f32_e32 v49, v49
	v_mul_f32_e32 v48, v51, v55
	v_add_f32_e32 v59, 1.0, v59
	v_add_f32_e32 v49, 1.0, v49
	v_rcp_f32_e32 v59, v59
	v_rcp_f32_e32 v49, v49
	v_mul_f32_e32 v59, v59, v60
	v_mul_f32_e32 v51, v49, v48
	v_cvt_pk_bf16_f32 v48, v56, v57
	v_cvt_pk_bf16_f32 v49, v58, v59
	v_cvt_pk_bf16_f32 v50, v52, v53
	v_add_co_u32_e32 v52, vcc, s66, v140
	v_cvt_pk_bf16_f32 v51, v54, v51
	s_nop 1
	v_addc_co_u32_e32 v53, vcc, 0, v141, vcc
	global_store_dwordx4 v[52:53], v[48:51], off
	v_mul_f32_e32 v44, v40, v44
	v_mul_f32_e32 v40, 0xbfb8aa3b, v40
	v_mul_f32_e32 v36, v32, v36
	v_mul_f32_e32 v32, 0xbfb8aa3b, v32
	v_exp_f32_e32 v40, v40
	v_exp_f32_e32 v32, v32
	v_add_f32_e32 v40, 1.0, v40
	v_add_f32_e32 v32, 1.0, v32
	v_rcp_f32_e32 v40, v40
	v_rcp_f32_e32 v32, v32
	v_mul_f32_e32 v40, v40, v44
	v_mul_f32_e32 v44, v41, v45
	v_mul_f32_e32 v41, 0xbfb8aa3b, v41
	v_mul_f32_e32 v36, v32, v36
	v_mul_f32_e32 v32, v33, v37
	v_mul_f32_e32 v33, 0xbfb8aa3b, v33
	v_exp_f32_e32 v41, v41
	v_exp_f32_e32 v33, v33
	v_add_f32_e32 v41, 1.0, v41
	v_add_f32_e32 v33, 1.0, v33
	v_rcp_f32_e32 v41, v41
	v_rcp_f32_e32 v33, v33
	v_mul_f32_e32 v41, v41, v44
	v_mul_f32_e32 v44, v42, v46
	v_mul_f32_e32 v42, 0xbfb8aa3b, v42
	v_mul_f32_e32 v37, v33, v32
	v_mul_f32_e32 v33, 0xbfb8aa3b, v34
	v_exp_f32_e32 v42, v42
	v_exp_f32_e32 v33, v33
	v_mul_f32_e32 v32, v34, v38
	v_add_f32_e32 v42, 1.0, v42
	v_add_f32_e32 v33, 1.0, v33
	v_rcp_f32_e32 v42, v42
; #define SBAR() __builtin_amdgcn_sched_barrier(0)
; template <int EPI, int N, int K>
; __device__ __forceinline__ void phase_gemm(const Params& p, const u16* __restrict__ A, const u16* __restrict__ Bt, int nM, char* shm,
;                            u16* __restrict__ outp, float* __restrict__ rowss) {
;     ...
;     if constexpr (EPI == EPI_SWIGLU) {
;       u16* ob = outp + (size_t)((unsigned)(brow + wr * 64 + fr) * DFF + (unsigned)(pn * 128 + wc * 32 + fq * 8));
; #pragma unroll
;       for (int ai = 0; ai < 2; ++ai)
; #pragma unroll
;         for (int m = 0; m < 4; ++m) {
;           float hv[8];
; #pragma unroll
;           for (int n = 0; n < 2; ++n)
; #pragma unroll
;             for (int j = 0; j < 4; ++j) {
;               float g = acc[ai][0][m][n][j], u = acc[ai][1][m][n][j];
;               hv[n * 4 + j] = g * u * __builtin_amdgcn_rcpf(1.f + __builtin_amdgcn_exp2f(-1.4426950408889634f * g));
;             }
;           u32x4 w = {cvtpk(hv[0], hv[1]), cvtpk(hv[2], hv[3]), cvtpk(hv[4], hv[5]), cvtpk(hv[6], hv[7])};
;           *(u32x4*)(ob + (ai * 128 + m * 16) * DFF) = w;
;           SBAR();
;         }
;     ...
;     if (!more) break;
;     v = vn; pm = pmn; pn = pnn; A0 = A0n; B0p = B0n;
	v_rcp_f32_e32 v33, v33
	v_mul_f32_e32 v42, v42, v44
	v_mul_f32_e32 v44, v43, v47
	v_mul_f32_e32 v43, 0xbfb8aa3b, v43
	v_mul_f32_e32 v38, v33, v32
	v_mul_f32_e32 v33, 0xbfb8aa3b, v35
	v_exp_f32_e32 v43, v43
	v_exp_f32_e32 v33, v33
	v_mul_f32_e32 v32, v35, v39
	v_add_f32_e32 v43, 1.0, v43
	v_add_f32_e32 v33, 1.0, v33
	v_rcp_f32_e32 v43, v43
	v_rcp_f32_e32 v33, v33
	v_mul_f32_e32 v43, v43, v44
	v_mul_f32_e32 v35, v33, v32
	v_cvt_pk_bf16_f32 v32, v40, v41
	v_cvt_pk_bf16_f32 v33, v42, v43
	v_cvt_pk_bf16_f32 v34, v36, v37
	v_add_co_u32_e32 v36, vcc, s67, v140
	v_cvt_pk_bf16_f32 v35, v38, v35
	s_nop 1
	v_addc_co_u32_e32 v37, vcc, 0, v141, vcc
	global_store_dwordx4 v[36:37], v[32:35], off
	v_mul_f32_e32 v28, v24, v28
	v_mul_f32_e32 v24, 0xbfb8aa3b, v24
	v_mul_f32_e32 v20, v16, v20
	v_mul_f32_e32 v16, 0xbfb8aa3b, v16
	v_exp_f32_e32 v24, v24
	v_exp_f32_e32 v16, v16
	v_add_f32_e32 v24, 1.0, v24
	v_add_f32_e32 v16, 1.0, v16
	v_rcp_f32_e32 v24, v24
	v_rcp_f32_e32 v16, v16
	v_mul_f32_e32 v24, v24, v28
	v_mul_f32_e32 v28, v25, v29
	v_mul_f32_e32 v25, 0xbfb8aa3b, v25
	v_mul_f32_e32 v20, v16, v20
	v_mul_f32_e32 v16, v17, v21
	v_mul_f32_e32 v17, 0xbfb8aa3b, v17
	v_exp_f32_e32 v25, v25
	v_exp_f32_e32 v17, v17
	v_add_f32_e32 v25, 1.0, v25
	v_add_f32_e32 v17, 1.0, v17
	v_rcp_f32_e32 v25, v25
	v_rcp_f32_e32 v17, v17
	v_mul_f32_e32 v25, v25, v28
	v_mul_f32_e32 v28, v26, v30
	v_mul_f32_e32 v26, 0xbfb8aa3b, v26
	v_mul_f32_e32 v21, v17, v16
	v_mul_f32_e32 v17, 0xbfb8aa3b, v18
	v_exp_f32_e32 v26, v26
	v_exp_f32_e32 v17, v17
	v_mul_f32_e32 v16, v18, v22
	v_add_f32_e32 v26, 1.0, v26
	v_add_f32_e32 v17, 1.0, v17
	v_rcp_f32_e32 v26, v26
	v_rcp_f32_e32 v17, v17
	v_mul_f32_e32 v26, v26, v28
	v_mul_f32_e32 v28, v27, v31
	v_mul_f32_e32 v27, 0xbfb8aa3b, v27
	v_mul_f32_e32 v22, v17, v16
	v_mul_f32_e32 v17, 0xbfb8aa3b, v19
	v_exp_f32_e32 v27, v27
	v_exp_f32_e32 v17, v17
	v_mul_f32_e32 v16, v19, v23
	v_add_f32_e32 v27, 1.0, v27
	v_add_f32_e32 v17, 1.0, v17
	v_rcp_f32_e32 v27, v27
	v_rcp_f32_e32 v17, v17
	v_mul_f32_e32 v27, v27, v28
	v_mul_f32_e32 v19, v17, v16
	v_cvt_pk_bf16_f32 v16, v24, v25
	v_cvt_pk_bf16_f32 v17, v26, v27
	v_cvt_pk_bf16_f32 v18, v20, v21
	v_add_co_u32_e32 v20, vcc, s69, v140
	v_cvt_pk_bf16_f32 v19, v22, v19
	s_nop 1
	v_addc_co_u32_e32 v21, vcc, 0, v141, vcc
	global_store_dwordx4 v[20:21], v[16:19], off
	v_mul_f32_e32 v12, v8, v12
	v_mul_f32_e32 v8, 0xbfb8aa3b, v8
	v_mul_f32_e32 v4, v0, v4
	v_mul_f32_e32 v0, 0xbfb8aa3b, v0
	v_exp_f32_e32 v8, v8
	v_exp_f32_e32 v0, v0
	v_add_f32_e32 v8, 1.0, v8
	v_add_f32_e32 v0, 1.0, v0
	v_rcp_f32_e32 v8, v8
	v_rcp_f32_e32 v0, v0
	v_mul_f32_e32 v8, v8, v12
	v_mul_f32_e32 v12, v9, v13
	v_mul_f32_e32 v9, 0xbfb8aa3b, v9
	v_mul_f32_e32 v4, v0, v4
	v_mul_f32_e32 v0, v1, v5
	v_mul_f32_e32 v1, 0xbfb8aa3b, v1
	v_exp_f32_e32 v9, v9
	v_exp_f32_e32 v1, v1
	v_add_f32_e32 v9, 1.0, v9
	v_add_f32_e32 v1, 1.0, v1
	v_rcp_f32_e32 v9, v9
	v_rcp_f32_e32 v1, v1
	v_mul_f32_e32 v9, v9, v12
	v_mul_f32_e32 v12, v10, v14
	v_mul_f32_e32 v10, 0xbfb8aa3b, v10
	v_mul_f32_e32 v5, v1, v0
	v_mul_f32_e32 v1, 0xbfb8aa3b, v2
	v_exp_f32_e32 v10, v10
	v_exp_f32_e32 v1, v1
	v_mul_f32_e32 v0, v2, v6
	v_add_f32_e32 v10, 1.0, v10
	v_add_f32_e32 v1, 1.0, v1
	v_rcp_f32_e32 v10, v10
	v_rcp_f32_e32 v1, v1
	v_mul_f32_e32 v10, v10, v12
	v_mul_f32_e32 v12, v11, v15
	v_mul_f32_e32 v11, 0xbfb8aa3b, v11
	v_mul_f32_e32 v6, v1, v0
	v_mul_f32_e32 v1, 0xbfb8aa3b, v3
	v_exp_f32_e32 v11, v11
	v_exp_f32_e32 v1, v1
	v_mul_f32_e32 v0, v3, v7
	v_add_f32_e32 v11, 1.0, v11
	v_add_f32_e32 v1, 1.0, v1
	v_rcp_f32_e32 v11, v11
	v_rcp_f32_e32 v1, v1
	v_mul_f32_e32 v11, v11, v12
	v_mul_f32_e32 v3, v1, v0
	v_cvt_pk_bf16_f32 v0, v8, v9
	v_cvt_pk_bf16_f32 v1, v10, v11
	v_cvt_pk_bf16_f32 v2, v4, v5
	v_add_co_u32_e32 v4, vcc, 0xf2000, v140
	v_cvt_pk_bf16_f32 v3, v6, v3
	s_nop 1
	v_addc_co_u32_e32 v5, vcc, 0, v141, vcc
	global_store_dwordx4 v[4:5], v[0:3], off
	s_andn2_b64 vcc, exec, s[14:15]
	s_mov_b32 s31, s17
	s_mov_b32 s52, s16
	s_cbranch_vccz .LBB0_558
	s_waitcnt vmcnt(8)

; #define WAIT_V(n) asm volatile("s_waitcnt vmcnt(%0)" ::"n"(n) : "memory")
; #define WAIT_L(n) asm volatile("s_waitcnt lgkmcnt(%0)" ::"n"(n) : "memory")
; #define SBAR() __builtin_amdgcn_sched_barrier(0)
; #define STAGE(P, base, kt) do { _Pragma("unroll") for (int _i = 0; _i < 2; ++_i)                                        \
;       __builtin_amdgcn_global_load_lds((const unsigned*)((base) + (size_t)(sOff[_i] + (unsigned)(kt) * (BK * 2))),        \
;                                        (unsigned*)((P) + wid * 1024 + _i * 8192), 16, 0, 0); } while (0)
; #define LDA(dst, b, h) _Pragma("unroll") for (int m = 0; m < 4; ++m) _Pragma("unroll") for (int k = 0; k < 2; ++k) \
;       dst[m][k] = *(const bf16x8*)(SA(b, h) + aoff + (m * 2048 + k * 1024))
; #define LDB(dst, b, h) _Pragma("unroll") for (int n = 0; n < 2; ++n) _Pragma("unroll") for (int k = 0; k < 2; ++k) \
;       dst[n][k] = *(const bf16x8*)(SB(b, h) + boff + (n * 256 + k * 1024))
; #define BAR __builtin_amdgcn_s_barrier()
; template <int EPI, int N, int K>
; __device__ __forceinline__ void phase_gemm(const Params& p, const u16* __restrict__ A, const u16* __restrict__ Bt, int nM, char* shm,
;                            u16* __restrict__ outp, float* __restrict__ rowss) {
;     ...
;   for (;;) {
;     const char* A1 = A0 + (size_t)128 * K * 2;
;     const char* B1p = B0p + (size_t)128 * K * 2;
;     f32x4 acc[2][2][4][2] = {};
;     bf16x8 At[4][2], B0[2][2], B1[2][2];
;     if (wr == 1) BAR;
;     WAIT_V(0); BAR;
;     BAR;
;     for (int t = 0; t < nt - 2; t += 2) {
;       LDB(B0, 0, 0); SBAR(); LDA(At, 0, 0); STAGE(SA(1, 1), A1, t + 1);
;       WAIT_L(8); BAR; WAIT_L(0); MMA(0, 0, At, B0); BAR; SBAR();
;       LDB(B1, 0, 1); STAGE(SB(0, 0), B0p, t + 2);
;       BAR; WAIT_L(0); MMA(0, 1, At, B1); BAR;
;       LDA(At, 0, 1); STAGE(SA(0, 0), A0, t + 2);
;       BAR; WAIT_L(0); MMA(1, 0, At, B0); BAR; SBAR();
;       STAGE(SB(0, 1), B1p, t + 2);
;       WAIT_V(6); BAR; MMA(1, 1, At, B1); BAR;
.LBB0_552:
	s_add_u32 s14, s8, 0x40000
	s_addc_u32 s15, s9, 0
	s_add_u32 s16, s6, 0x40000
	s_addc_u32 s17, s7, 0
	s_mov_b32 s53, -2
	v_mov_b32_e32 v140, v146
	v_mov_b32_e32 v141, v145
	s_barrier
	s_barrier
	v_or_b32_e32 v147, 0x10000, v143
	v_add_u32_e32 v149, 0x10100, v143
	v_add_u32_e32 v148, 0x10400, v143
	ds_read_b128 v[156:159], v147
	ds_read_b128 v[160:163], v148
	v_add_u32_e32 v150, 0x10500, v143
	ds_read_b128 v[164:167], v149
	ds_read_b128 v[168:171], v150
	v_add_u32_e32 v196, v142, v140
	s_add_i32 s55, s19, 0xc000
	v_add_u32_e32 v151, 0x80, v196
	s_mov_b32 m0, s55
	v_add_u32_e32 v197, v142, v141
	s_add_i32 s54, s19, 0xe000
	ds_read_b128 v[172:175], v144
	ds_read_b128 v[176:179], v144 offset:1024
	ds_read_b128 v[180:183], v144 offset:2048
	ds_read_b128 v[208:211], v144 offset:3072
	ds_read_b128 v[212:215], v144 offset:4096
	ds_read_b128 v[216:219], v144 offset:5120
	ds_read_b128 v[220:223], v144 offset:6144
	ds_read_b128 v[224:227], v144 offset:7168
	global_load_lds_dwordx4 v151, s[14:15]
	v_add_u32_e32 v151, 0x80, v197
	s_mov_b32 m0, s54
	s_nop 0
	global_load_lds_dwordx4 v151, s[14:15]
	s_waitcnt lgkmcnt(8)
	s_barrier
	s_waitcnt lgkmcnt(0)
	s_waitcnt lgkmcnt(0)
	v_mfma_f32_16x16x32_bf16 v[126:129], v[156:159], v[172:175], 0
	v_mfma_f32_16x16x32_bf16 v[122:125], v[164:167], v[172:175], 0
	v_mfma_f32_16x16x32_bf16 v[118:121], v[156:159], v[180:183], 0
	v_mfma_f32_16x16x32_bf16 v[114:117], v[164:167], v[180:183], 0
	v_mfma_f32_16x16x32_bf16 v[110:113], v[156:159], v[212:215], 0
	v_mfma_f32_16x16x32_bf16 v[106:109], v[164:167], v[212:215], 0
	v_mfma_f32_16x16x32_bf16 v[102:105], v[156:159], v[220:223], 0
	v_mfma_f32_16x16x32_bf16 v[98:101], v[164:167], v[220:223], 0
	v_mfma_f32_16x16x32_bf16 v[126:129], v[160:163], v[176:179], v[126:129]
	v_mfma_f32_16x16x32_bf16 v[122:125], v[168:171], v[176:179], v[122:125]
	v_mfma_f32_16x16x32_bf16 v[118:121], v[160:163], v[208:211], v[118:121]
	v_mfma_f32_16x16x32_bf16 v[114:117], v[168:171], v[208:211], v[114:117]
	v_mfma_f32_16x16x32_bf16 v[110:113], v[160:163], v[216:219], v[110:113]
	v_mfma_f32_16x16x32_bf16 v[106:109], v[168:171], v[216:219], v[106:109]
	v_mfma_f32_16x16x32_bf16 v[102:105], v[160:163], v[224:227], v[102:105]
	v_mfma_f32_16x16x32_bf16 v[98:101], v[168:171], v[224:227], v[98:101]
	s_barrier
	s_mov_b32 m0, s23
	v_or_b32_e32 v151, 0x14000, v143
	v_add_u32_e32 v153, 0x14100, v143
	v_add_u32_e32 v198, 0x100, v196
	v_add_u32_e32 v152, 0x14400, v143
	ds_read_b128 v[228:231], v151
	ds_read_b128 v[232:235], v152
	v_add_u32_e32 v154, 0x14500, v143
	ds_read_b128 v[236:239], v153
	ds_read_b128 v[240:243], v154
	global_load_lds_dwordx4 v198, s[6:7]
	v_add_u32_e32 v199, 0x100, v197
	s_mov_b32 m0, s92
	s_nop 0
	global_load_lds_dwordx4 v199, s[6:7]
	s_barrier
	s_waitcnt lgkmcnt(0)
	s_waitcnt lgkmcnt(0)
	v_mfma_f32_16x16x32_bf16 v[92:95], v[228:231], v[172:175], 0
	v_mfma_f32_16x16x32_bf16 v[88:91], v[236:239], v[172:175], 0
	v_mfma_f32_16x16x32_bf16 v[84:87], v[228:231], v[180:183], 0
	v_mfma_f32_16x16x32_bf16 v[80:83], v[236:239], v[180:183], 0
	v_mfma_f32_16x16x32_bf16 v[76:79], v[228:231], v[212:215], 0
	v_mfma_f32_16x16x32_bf16 v[72:75], v[236:239], v[212:215], 0
	v_mfma_f32_16x16x32_bf16 v[68:71], v[228:231], v[220:223], 0
	v_mfma_f32_16x16x32_bf16 v[64:67], v[236:239], v[220:223], 0
	v_mfma_f32_16x16x32_bf16 v[92:95], v[232:235], v[176:179], v[92:95]
	v_mfma_f32_16x16x32_bf16 v[88:91], v[240:243], v[176:179], v[88:91]
	v_mfma_f32_16x16x32_bf16 v[84:87], v[232:235], v[208:211], v[84:87]
	v_mfma_f32_16x16x32_bf16 v[80:83], v[240:243], v[208:211], v[80:83]
	v_mfma_f32_16x16x32_bf16 v[76:79], v[232:235], v[216:219], v[76:79]
	v_mfma_f32_16x16x32_bf16 v[72:75], v[240:243], v[216:219], v[72:75]
	v_mfma_f32_16x16x32_bf16 v[68:71], v[232:235], v[224:227], v[68:71]
	v_mfma_f32_16x16x32_bf16 v[64:67], v[240:243], v[224:227], v[64:67]
	s_mov_b32 m0, s19
	s_barrier
	ds_read_b128 v[172:175], v144 offset:16384
	ds_read_b128 v[176:179], v144 offset:17408
	ds_read_b128 v[180:183], v144 offset:18432
	ds_read_b128 v[208:211], v144 offset:19456
	ds_read_b128 v[212:215], v144 offset:20480
	ds_read_b128 v[216:219], v144 offset:21504
	ds_read_b128 v[220:223], v144 offset:22528
	ds_read_b128 v[224:227], v144 offset:23552
	global_load_lds_dwordx4 v198, s[8:9]
	s_mov_b32 m0, s22
	s_nop 0
	global_load_lds_dwordx4 v199, s[8:9]
	s_barrier
	s_waitcnt lgkmcnt(0)
	s_waitcnt lgkmcnt(0)
	v_mfma_f32_16x16x32_bf16 v[60:63], v[156:159], v[172:175], 0
	v_mfma_f32_16x16x32_bf16 v[56:59], v[164:167], v[172:175], 0
	v_mfma_f32_16x16x32_bf16 v[52:55], v[156:159], v[180:183], 0
	v_mfma_f32_16x16x32_bf16 v[48:51], v[164:167], v[180:183], 0
	v_mfma_f32_16x16x32_bf16 v[44:47], v[156:159], v[212:215], 0
	v_mfma_f32_16x16x32_bf16 v[40:43], v[164:167], v[212:215], 0
	v_mfma_f32_16x16x32_bf16 v[36:39], v[156:159], v[220:223], 0
	v_mfma_f32_16x16x32_bf16 v[32:35], v[164:167], v[220:223], 0
	v_mfma_f32_16x16x32_bf16 v[60:63], v[160:163], v[176:179], v[60:63]
	v_mfma_f32_16x16x32_bf16 v[56:59], v[168:171], v[176:179], v[56:59]
	v_mfma_f32_16x16x32_bf16 v[52:55], v[160:163], v[208:211], v[52:55]
	v_mfma_f32_16x16x32_bf16 v[48:51], v[168:171], v[208:211], v[48:51]
	v_mfma_f32_16x16x32_bf16 v[44:47], v[160:163], v[216:219], v[44:47]
	v_mfma_f32_16x16x32_bf16 v[40:43], v[168:171], v[216:219], v[40:43]
	v_mfma_f32_16x16x32_bf16 v[36:39], v[160:163], v[224:227], v[36:39]
	v_mfma_f32_16x16x32_bf16 v[32:35], v[168:171], v[224:227], v[32:35]
	s_barrier
	s_mov_b32 m0, s94
	s_nop 0
	global_load_lds_dwordx4 v198, s[16:17]
	s_mov_b32 m0, s95
	s_nop 0
	global_load_lds_dwordx4 v199, s[16:17]
	s_waitcnt vmcnt(6)
	s_barrier
; #define WAIT_V(n) asm volatile("s_waitcnt vmcnt(%0)" ::"n"(n) : "memory")
; #define WAIT_L(n) asm volatile("s_waitcnt lgkmcnt(%0)" ::"n"(n) : "memory")
; #define SBAR() __builtin_amdgcn_sched_barrier(0)
; #define STAGE(P, base, kt) do { _Pragma("unroll") for (int _i = 0; _i < 2; ++_i)                                        \
;       __builtin_amdgcn_global_load_lds((const unsigned*)((base) + (size_t)(sOff[_i] + (unsigned)(kt) * (BK * 2))),        \
;                                        (unsigned*)((P) + wid * 1024 + _i * 8192), 16, 0, 0); } while (0)
; #define LDA(dst, b, h) _Pragma("unroll") for (int m = 0; m < 4; ++m) _Pragma("unroll") for (int k = 0; k < 2; ++k) \
;       dst[m][k] = *(const bf16x8*)(SA(b, h) + aoff + (m * 2048 + k * 1024))
; #define LDB(dst, b, h) _Pragma("unroll") for (int n = 0; n < 2; ++n) _Pragma("unroll") for (int k = 0; k < 2; ++k) \
;       dst[n][k] = *(const bf16x8*)(SB(b, h) + boff + (n * 256 + k * 1024))
; #define BAR __builtin_amdgcn_s_barrier()
; template <int EPI, int N, int K>
; __device__ __forceinline__ void phase_gemm(const Params& p, const u16* __restrict__ A, const u16* __restrict__ Bt, int nM, char* shm,
;                            u16* __restrict__ outp, float* __restrict__ rowss) {
;     ...
;       WAIT_V(6); BAR; MMA(1, 1, At, B1); BAR;
;       LDB(B0, 1, 0); SBAR(); LDA(At, 1, 0); STAGE(SA(0, 1), A1, t + 2);
;       WAIT_L(8); BAR; WAIT_L(0); MMA(0, 0, At, B0); BAR; SBAR();
;       LDB(B1, 1, 1); STAGE(SB(1, 0), B0p, t + 3);
;       BAR; WAIT_L(0); MMA(0, 1, At, B1); BAR;
;       LDA(At, 1, 1); STAGE(SA(1, 0), A0, t + 3);
;       BAR; WAIT_L(0); MMA(1, 0, At, B0); BAR; SBAR();
	v_mfma_f32_16x16x32_bf16 v[28:31], v[228:231], v[172:175], 0
	v_mfma_f32_16x16x32_bf16 v[24:27], v[236:239], v[172:175], 0
	v_mfma_f32_16x16x32_bf16 v[20:23], v[228:231], v[180:183], 0
	v_mfma_f32_16x16x32_bf16 v[16:19], v[236:239], v[180:183], 0
	v_mfma_f32_16x16x32_bf16 v[12:15], v[228:231], v[212:215], 0
	v_mfma_f32_16x16x32_bf16 v[8:11], v[236:239], v[212:215], 0
	v_mfma_f32_16x16x32_bf16 v[4:7], v[228:231], v[220:223], 0
	v_mfma_f32_16x16x32_bf16 v[0:3], v[236:239], v[220:223], 0
	v_mfma_f32_16x16x32_bf16 v[28:31], v[232:235], v[176:179], v[28:31]
	v_mfma_f32_16x16x32_bf16 v[24:27], v[240:243], v[176:179], v[24:27]
	v_mfma_f32_16x16x32_bf16 v[20:23], v[232:235], v[208:211], v[20:23]
	v_mfma_f32_16x16x32_bf16 v[16:19], v[240:243], v[208:211], v[16:19]
	v_mfma_f32_16x16x32_bf16 v[12:15], v[232:235], v[216:219], v[12:15]
	v_mfma_f32_16x16x32_bf16 v[8:11], v[240:243], v[216:219], v[8:11]
	v_mfma_f32_16x16x32_bf16 v[4:7], v[232:235], v[224:227], v[4:7]
	v_mfma_f32_16x16x32_bf16 v[0:3], v[240:243], v[224:227], v[0:3]
	v_or_b32_e32 v155, 0x18000, v143
	v_add_u32_e32 v157, 0x18100, v143
	s_barrier
	v_add_u32_e32 v156, 0x18400, v143
	ds_read_b128 v[164:167], v155
	ds_read_b128 v[168:171], v156
	v_add_u32_e32 v158, 0x18500, v143
	ds_read_b128 v[172:175], v157
	ds_read_b128 v[176:179], v158
	s_mov_b32 m0, s96
	ds_read_b128 v[180:183], v144 offset:32768
	ds_read_b128 v[208:211], v144 offset:33792
	ds_read_b128 v[212:215], v144 offset:34816
	ds_read_b128 v[216:219], v144 offset:35840
	ds_read_b128 v[220:223], v144 offset:36864
	ds_read_b128 v[224:227], v144 offset:37888
	ds_read_b128 v[228:231], v144 offset:38912
	ds_read_b128 v[232:235], v144 offset:39936
	global_load_lds_dwordx4 v198, s[14:15]
	s_mov_b32 m0, s33
	s_nop 0
	global_load_lds_dwordx4 v199, s[14:15]
	s_waitcnt lgkmcnt(8)
	s_barrier
	s_waitcnt lgkmcnt(0)
	s_waitcnt lgkmcnt(0)
	v_mfma_f32_16x16x32_bf16 v[126:129], v[164:167], v[180:183], v[126:129]
	v_mfma_f32_16x16x32_bf16 v[122:125], v[172:175], v[180:183], v[122:125]
	v_mfma_f32_16x16x32_bf16 v[118:121], v[164:167], v[212:215], v[118:121]
	v_mfma_f32_16x16x32_bf16 v[114:117], v[172:175], v[212:215], v[114:117]
	v_mfma_f32_16x16x32_bf16 v[110:113], v[164:167], v[220:223], v[110:113]
	v_mfma_f32_16x16x32_bf16 v[106:109], v[172:175], v[220:223], v[106:109]
	v_mfma_f32_16x16x32_bf16 v[102:105], v[164:167], v[228:231], v[102:105]
	v_mfma_f32_16x16x32_bf16 v[98:101], v[172:175], v[228:231], v[98:101]
	v_mfma_f32_16x16x32_bf16 v[126:129], v[168:171], v[208:211], v[126:129]
	v_mfma_f32_16x16x32_bf16 v[122:125], v[176:179], v[208:211], v[122:125]
	v_mfma_f32_16x16x32_bf16 v[118:121], v[168:171], v[216:219], v[118:121]
	v_mfma_f32_16x16x32_bf16 v[114:117], v[176:179], v[216:219], v[114:117]
	v_mfma_f32_16x16x32_bf16 v[110:113], v[168:171], v[224:227], v[110:113]
	v_mfma_f32_16x16x32_bf16 v[106:109], v[176:179], v[224:227], v[106:109]
	v_mfma_f32_16x16x32_bf16 v[102:105], v[168:171], v[232:235], v[102:105]
	v_mfma_f32_16x16x32_bf16 v[98:101], v[176:179], v[232:235], v[98:101]
	s_barrier
	s_mov_b32 m0, s35
	v_or_b32_e32 v159, 0x1c000, v143
	v_add_u32_e32 v161, 0x1c100, v143
	v_add_u32_e32 v163, 0x180, v196
	v_add_u32_e32 v160, 0x1c400, v143
	ds_read_b128 v[236:239], v159
	ds_read_b128 v[240:243], v160
	v_add_u32_e32 v162, 0x1c500, v143
	ds_read_b128 v[244:247], v161
	ds_read_b128 v[248:251], v162
	global_load_lds_dwordx4 v163, s[6:7]
	v_add_u32_e32 v196, 0x180, v197
	s_mov_b32 m0, s93
	s_nop 0
	global_load_lds_dwordx4 v196, s[6:7]
	s_barrier
; #define WAIT_V(n) asm volatile("s_waitcnt vmcnt(%0)" ::"n"(n) : "memory")
; #define WAIT_L(n) asm volatile("s_waitcnt lgkmcnt(%0)" ::"n"(n) : "memory")
; #define SBAR() __builtin_amdgcn_sched_barrier(0)
; #define STAGE(P, base, kt) do { _Pragma("unroll") for (int _i = 0; _i < 2; ++_i)                                        \
;       __builtin_amdgcn_global_load_lds((const unsigned*)((base) + (size_t)(sOff[_i] + (unsigned)(kt) * (BK * 2))),        \
;                                        (unsigned*)((P) + wid * 1024 + _i * 8192), 16, 0, 0); } while (0)
; #define BAR __builtin_amdgcn_s_barrier()
; template <int EPI, int N, int K>
; __device__ __forceinline__ void phase_gemm(const Params& p, const u16* __restrict__ A, const u16* __restrict__ Bt, int nM, char* shm,
;                            u16* __restrict__ outp, float* __restrict__ rowss) {
;     ...
;       BAR; WAIT_L(0); MMA(1, 0, At, B0); BAR; SBAR();
;       STAGE(SB(1, 1), B1p, t + 3);
;       WAIT_V(6); BAR; MMA(1, 1, At, B1); BAR;
;     }
	s_waitcnt lgkmcnt(0)
	s_waitcnt lgkmcnt(0)
	v_mfma_f32_16x16x32_bf16 v[92:95], v[236:239], v[180:183], v[92:95]
	v_mfma_f32_16x16x32_bf16 v[88:91], v[244:247], v[180:183], v[88:91]
	v_mfma_f32_16x16x32_bf16 v[84:87], v[236:239], v[212:215], v[84:87]
	v_mfma_f32_16x16x32_bf16 v[80:83], v[244:247], v[212:215], v[80:83]
	v_mfma_f32_16x16x32_bf16 v[76:79], v[236:239], v[220:223], v[76:79]
	v_mfma_f32_16x16x32_bf16 v[72:75], v[244:247], v[220:223], v[72:75]
	v_mfma_f32_16x16x32_bf16 v[68:71], v[236:239], v[228:231], v[68:71]
	v_mfma_f32_16x16x32_bf16 v[64:67], v[244:247], v[228:231], v[64:67]
	v_mfma_f32_16x16x32_bf16 v[92:95], v[240:243], v[208:211], v[92:95]
	v_mfma_f32_16x16x32_bf16 v[88:91], v[248:251], v[208:211], v[88:91]
	v_mfma_f32_16x16x32_bf16 v[84:87], v[240:243], v[216:219], v[84:87]
	v_mfma_f32_16x16x32_bf16 v[80:83], v[248:251], v[216:219], v[80:83]
	v_mfma_f32_16x16x32_bf16 v[76:79], v[240:243], v[224:227], v[76:79]
	v_mfma_f32_16x16x32_bf16 v[72:75], v[248:251], v[224:227], v[72:75]
	v_mfma_f32_16x16x32_bf16 v[68:71], v[240:243], v[232:235], v[68:71]
	v_mfma_f32_16x16x32_bf16 v[64:67], v[248:251], v[232:235], v[64:67]
	s_mov_b32 m0, s24
	s_barrier
	ds_read_b128 v[180:183], v144 offset:49152
	ds_read_b128 v[208:211], v144 offset:50176
	ds_read_b128 v[212:215], v144 offset:51200
	ds_read_b128 v[216:219], v144 offset:52224
	ds_read_b128 v[220:223], v144 offset:53248
	ds_read_b128 v[224:227], v144 offset:54272
	ds_read_b128 v[228:231], v144 offset:55296
	ds_read_b128 v[232:235], v144 offset:56320
	global_load_lds_dwordx4 v163, s[8:9]
	s_mov_b32 m0, s25
	s_nop 0
	global_load_lds_dwordx4 v196, s[8:9]
	s_barrier
	s_waitcnt lgkmcnt(0)
	s_waitcnt lgkmcnt(0)
	v_mfma_f32_16x16x32_bf16 v[60:63], v[164:167], v[180:183], v[60:63]
	v_mfma_f32_16x16x32_bf16 v[56:59], v[172:175], v[180:183], v[56:59]
	v_mfma_f32_16x16x32_bf16 v[52:55], v[164:167], v[212:215], v[52:55]
	v_mfma_f32_16x16x32_bf16 v[48:51], v[172:175], v[212:215], v[48:51]
	v_mfma_f32_16x16x32_bf16 v[44:47], v[164:167], v[220:223], v[44:47]
	v_mfma_f32_16x16x32_bf16 v[40:43], v[172:175], v[220:223], v[40:43]
	v_mfma_f32_16x16x32_bf16 v[36:39], v[164:167], v[228:231], v[36:39]
	v_mfma_f32_16x16x32_bf16 v[32:35], v[172:175], v[228:231], v[32:35]
	v_mfma_f32_16x16x32_bf16 v[60:63], v[168:171], v[208:211], v[60:63]
	v_mfma_f32_16x16x32_bf16 v[56:59], v[176:179], v[208:211], v[56:59]
	v_mfma_f32_16x16x32_bf16 v[52:55], v[168:171], v[216:219], v[52:55]
	v_mfma_f32_16x16x32_bf16 v[48:51], v[176:179], v[216:219], v[48:51]
	v_mfma_f32_16x16x32_bf16 v[44:47], v[168:171], v[224:227], v[44:47]
	v_mfma_f32_16x16x32_bf16 v[40:43], v[176:179], v[224:227], v[40:43]
	v_mfma_f32_16x16x32_bf16 v[36:39], v[168:171], v[232:235], v[36:39]
	v_mfma_f32_16x16x32_bf16 v[32:35], v[176:179], v[232:235], v[32:35]
	s_barrier
	s_mov_b32 m0, s26
	s_nop 0
	global_load_lds_dwordx4 v163, s[16:17]
	s_mov_b32 m0, s27
	s_nop 0
	global_load_lds_dwordx4 v196, s[16:17]
	s_waitcnt vmcnt(6)
	s_barrier
	v_mfma_f32_16x16x32_bf16 v[28:31], v[236:239], v[180:183], v[28:31]
	v_mfma_f32_16x16x32_bf16 v[24:27], v[244:247], v[180:183], v[24:27]
	v_mfma_f32_16x16x32_bf16 v[20:23], v[236:239], v[212:215], v[20:23]
	v_mfma_f32_16x16x32_bf16 v[16:19], v[244:247], v[212:215], v[16:19]
	v_mfma_f32_16x16x32_bf16 v[12:15], v[236:239], v[220:223], v[12:15]
	v_mfma_f32_16x16x32_bf16 v[8:11], v[244:247], v[220:223], v[8:11]
	v_mfma_f32_16x16x32_bf16 v[4:7], v[236:239], v[228:231], v[4:7]
	v_mfma_f32_16x16x32_bf16 v[0:3], v[244:247], v[228:231], v[0:3]
	v_mfma_f32_16x16x32_bf16 v[28:31], v[240:243], v[208:211], v[28:31]
	v_mfma_f32_16x16x32_bf16 v[24:27], v[248:251], v[208:211], v[24:27]
	v_mfma_f32_16x16x32_bf16 v[20:23], v[240:243], v[216:219], v[20:23]
	v_mfma_f32_16x16x32_bf16 v[16:19], v[248:251], v[216:219], v[16:19]
	v_mfma_f32_16x16x32_bf16 v[12:15], v[240:243], v[224:227], v[12:15]
	v_mfma_f32_16x16x32_bf16 v[8:11], v[248:251], v[224:227], v[8:11]
	v_mfma_f32_16x16x32_bf16 v[4:7], v[240:243], v[232:235], v[4:7]
	v_mfma_f32_16x16x32_bf16 v[0:3], v[248:251], v[232:235], v[0:3]
	s_add_i32 s53, s53, 2
	v_add_u32_e32 v141, 0x100, v141
	s_cmp_lt_u32 s53, 12
	v_add_u32_e32 v140, 0x100, v140
	s_barrier
